# gdn conv stage: the q/k l2-norm 8-lane reductions use DPP adds instead of ds_bpermute round trips (same association)
# speedup vs baseline: 1.0062x; 1.0016x over previous
; #define LAS __attribute__((address_space(3)))
; __device__ __forceinline__ float silu_acc(float x) { return x * frcp(1.0f + fexp(-x)); }
; __device__ __forceinline__ void gdn_unit(const Ctx& X, LAS unsigned char* hl, int b, int c, int h, int tid_h, int w4, int lane, int layer) {
;     ...
;         for (int rs = 0; rs < 2; ++rs) {
;             const int i = i0 + 32 * rs;
;             const float bi = Bs[i], Gi = Gs[i];
;             float y[3][8];
; #pragma unroll
;             for (int tn = 0; tn < 3; ++tn) {
; #pragma unroll
;                 for (int e = 0; e < 8; ++e) y[tn][e] = 0.f;
; #pragma unroll
;                 for (int k = 0; k < 4; ++k) { float x8[8]; unpack8(*(const LAS u32x4*)(RAW + (tn * 67 + i + k) * 64 + cseg * 8), x8);
;                     y[tn][0] += wq[tn][k][0].x * x8[0]; y[tn][1] += wq[tn][k][0].y * x8[1]; y[tn][2] += wq[tn][k][0].z * x8[2]; y[tn][3] += wq[tn][k][0].w * x8[3];
;                     y[tn][4] += wq[tn][k][1].x * x8[4]; y[tn][5] += wq[tn][k][1].y * x8[5]; y[tn][6] += wq[tn][k][1].z * x8[6]; y[tn][7] += wq[tn][k][1].w * x8[7]; }
; #pragma unroll
;                 for (int e = 0; e < 8; ++e) y[tn][e] = silu_acc(y[tn][e]);
;             }
.LpfG_done:
	v_add_u32_e32 v193, v182, v156
	v_cndmask_b32_e32 v102, v230, v102, vcc
	v_lshlrev_b32_e32 v197, 2, v102
	v_xor_b32_e32 v102, 2, v230
	v_cmp_lt_i32_e32 vcc, v102, v103
	v_add_u32_e32 v192, v189, v156
	v_add_u32_e32 v155, v183, v156
	v_add_u32_e32 v133, v181, v156
	v_lshl_add_u32 v156, v191, 7, v135
	ds_read_b32 v194, v185 offset:252
	v_cndmask_b32_e32 v102, v230, v102, vcc
	ds_read_b128 v[106:109], v156
	ds_read_b128 v[112:115], v156 offset:128
	v_lshlrev_b32_e32 v196, 2, v102
	v_xor_b32_e32 v102, 4, v230
	v_cmp_lt_i32_e32 vcc, v102, v103
	s_waitcnt lgkmcnt(1)
	v_lshlrev_b32_e32 v104, 16, v106
	s_waitcnt lgkmcnt(0)
	v_lshlrev_b32_e32 v105, 16, v112
	v_cndmask_b32_e32 v102, v230, v102, vcc
	v_lshlrev_b32_e32 v195, 2, v102
	v_lshlrev_b32_e32 v102, 2, v191
	v_add_u32_e32 v198, v188, v102
	v_add_u32_e32 v199, v185, v102
	v_mov_b32_e32 v102, v66
	v_mov_b32_e32 v103, v74
	v_pk_mul_f32 v[134:135], v[102:103], v[104:105]
	v_and_b32_e32 v105, 0xffff0000, v112
	v_and_b32_e32 v104, 0xffff0000, v106
	v_mov_b32_e32 v74, v67
	v_pk_mul_f32 v[136:137], v[74:75], v[104:105]
	v_lshlrev_b32_e32 v105, 16, v107
	v_lshlrev_b32_e32 v104, 16, v113
	v_mov_b32_e32 v66, v76
	v_mov_b32_e32 v67, v68
	ds_read_b32 v200, v198
	ds_read_b32 v201, v199
	v_pk_mul_f32 v[118:119], v[66:67], v[104:105]
	v_and_b32_e32 v105, 0xffff0000, v107
	v_and_b32_e32 v104, 0xffff0000, v113
	v_mov_b32_e32 v68, v77
	ds_read_b128 v[122:125], v156 offset:256
	ds_read_b128 v[126:129], v156 offset:384
	v_pk_mul_f32 v[120:121], v[68:69], v[104:105]
	v_lshlrev_b32_e32 v77, 16, v114
	v_lshlrev_b32_e32 v76, 16, v108
	v_mov_b32_e32 v104, v58
	v_mov_b32_e32 v105, v98
	v_pk_mul_f32 v[110:111], v[104:105], v[76:77]
	v_and_b32_e32 v77, 0xffff0000, v108
	v_and_b32_e32 v76, 0xffff0000, v114
	v_mov_b32_e32 v58, v99
	v_pk_mul_f32 v[112:113], v[58:59], v[76:77]
	v_lshlrev_b32_e32 v99, 16, v109
	v_lshlrev_b32_e32 v98, 16, v115
	v_mov_b32_e32 v76, v100
	v_mov_b32_e32 v77, v60
	v_pk_mul_f32 v[106:107], v[76:77], v[98:99]
	v_and_b32_e32 v99, 0xffff0000, v109
	v_and_b32_e32 v98, 0xffff0000, v115
	v_mov_b32_e32 v60, v101
	v_pk_mul_f32 v[108:109], v[60:61], v[98:99]
	s_waitcnt lgkmcnt(0)
	v_lshlrev_b32_e32 v101, 16, v126
	v_lshlrev_b32_e32 v100, 16, v122
	v_mov_b32_e32 v98, v62
	v_mov_b32_e32 v99, v70
	v_pk_mul_f32 v[150:151], v[98:99], v[100:101]
	v_and_b32_e32 v101, 0xffff0000, v126
	v_and_b32_e32 v100, 0xffff0000, v122
	v_mov_b32_e32 v70, v63
	v_pk_mul_f32 v[162:163], v[70:71], v[100:101]
	v_lshlrev_b32_e32 v101, 16, v123
	v_lshlrev_b32_e32 v100, 16, v127
	v_mov_b32_e32 v62, v72
	v_mov_b32_e32 v63, v64
	v_pk_mul_f32 v[138:139], v[62:63], v[100:101]
	v_and_b32_e32 v101, 0xffff0000, v123
	v_and_b32_e32 v100, 0xffff0000, v127
	v_mov_b32_e32 v64, v73
	ds_read_b128 v[144:147], v156 offset:8576
	ds_read_b128 v[164:167], v156 offset:8704
	v_pk_mul_f32 v[142:143], v[64:65], v[100:101]
	v_lshlrev_b32_e32 v73, 16, v128
	v_lshlrev_b32_e32 v72, 16, v124
	v_mov_b32_e32 v100, v54
	v_mov_b32_e32 v101, v94
	v_pk_mul_f32 v[122:123], v[100:101], v[72:73]
	v_and_b32_e32 v73, 0xffff0000, v124
	v_and_b32_e32 v72, 0xffff0000, v128
	v_mov_b32_e32 v54, v95
	v_pk_mul_f32 v[126:127], v[54:55], v[72:73]
	v_lshlrev_b32_e32 v95, 16, v125
	v_lshlrev_b32_e32 v94, 16, v129
	v_mov_b32_e32 v72, v96
	v_mov_b32_e32 v73, v56
	v_pk_mul_f32 v[114:115], v[72:73], v[94:95]
	v_and_b32_e32 v95, 0xffff0000, v125
	v_and_b32_e32 v94, 0xffff0000, v129
	v_mov_b32_e32 v56, v97
	v_pk_mul_f32 v[116:117], v[56:57], v[94:95]
	s_waitcnt lgkmcnt(0)
	v_lshlrev_b32_e32 v97, 16, v164
	v_lshlrev_b32_e32 v96, 16, v144
	v_mov_b32_e32 v94, v46
	v_mov_b32_e32 v95, v50
	v_pk_mul_f32 v[168:169], v[94:95], v[96:97]
	v_and_b32_e32 v97, 0xffff0000, v164
	v_and_b32_e32 v96, 0xffff0000, v144
	v_mov_b32_e32 v50, v47
	v_pk_mul_f32 v[170:171], v[50:51], v[96:97]
	v_lshlrev_b32_e32 v97, 16, v145
	v_lshlrev_b32_e32 v96, 16, v165
	v_mov_b32_e32 v46, v52
	v_mov_b32_e32 v47, v48
	v_pk_mul_f32 v[148:149], v[46:47], v[96:97]
	v_and_b32_e32 v97, 0xffff0000, v145
	v_and_b32_e32 v96, 0xffff0000, v165
	v_mov_b32_e32 v48, v53
	ds_read_b128 v[202:205], v156 offset:8832
	ds_read_b128 v[206:209], v156 offset:8960
	v_pk_mul_f32 v[152:153], v[48:49], v[96:97]
	v_lshlrev_b32_e32 v53, 16, v166
	v_lshlrev_b32_e32 v52, 16, v146
	v_mov_b32_e32 v96, v38
	v_mov_b32_e32 v97, v90
	v_pk_mul_f32 v[140:141], v[96:97], v[52:53]
	v_and_b32_e32 v53, 0xffff0000, v146
	v_and_b32_e32 v52, 0xffff0000, v166
	v_mov_b32_e32 v38, v91
	v_pk_mul_f32 v[144:145], v[38:39], v[52:53]
	v_lshlrev_b32_e32 v91, 16, v147
	v_lshlrev_b32_e32 v90, 16, v167
	v_mov_b32_e32 v52, v92
	v_mov_b32_e32 v53, v40
	v_pk_mul_f32 v[124:125], v[52:53], v[90:91]
	v_and_b32_e32 v91, 0xffff0000, v147
	v_and_b32_e32 v90, 0xffff0000, v167
	v_mov_b32_e32 v40, v93
	v_pk_mul_f32 v[128:129], v[40:41], v[90:91]
	s_waitcnt lgkmcnt(0)
	v_lshlrev_b32_e32 v93, 16, v206
	v_lshlrev_b32_e32 v92, 16, v202
	v_mov_b32_e32 v90, v34
	v_mov_b32_e32 v91, v42
	v_pk_mul_f32 v[176:177], v[90:91], v[92:93]
	v_and_b32_e32 v93, 0xffff0000, v206
	v_and_b32_e32 v92, 0xffff0000, v202
	v_mov_b32_e32 v42, v35
	v_pk_mul_f32 v[178:179], v[42:43], v[92:93]
	v_lshlrev_b32_e32 v93, 16, v203
	v_lshlrev_b32_e32 v92, 16, v207
	v_mov_b32_e32 v34, v44
	v_mov_b32_e32 v35, v36
	v_pk_mul_f32 v[172:173], v[34:35], v[92:93]
	v_and_b32_e32 v93, 0xffff0000, v203
	v_and_b32_e32 v92, 0xffff0000, v207
	v_mov_b32_e32 v36, v45
	ds_read_b128 v[210:213], v156 offset:17152
	ds_read_b128 v[214:217], v156 offset:17280
	v_pk_mul_f32 v[174:175], v[36:37], v[92:93]
	v_lshlrev_b32_e32 v45, 16, v208
	v_lshlrev_b32_e32 v44, 16, v204
	v_mov_b32_e32 v92, v30
	v_mov_b32_e32 v93, v86
	v_pk_mul_f32 v[164:165], v[92:93], v[44:45]
	v_and_b32_e32 v45, 0xffff0000, v204
	v_and_b32_e32 v44, 0xffff0000, v208
	v_mov_b32_e32 v30, v87
	v_pk_mul_f32 v[166:167], v[30:31], v[44:45]
	v_lshlrev_b32_e32 v87, 16, v205
	v_lshlrev_b32_e32 v86, 16, v209
	v_mov_b32_e32 v44, v88
	v_mov_b32_e32 v45, v32
	v_pk_mul_f32 v[146:147], v[44:45], v[86:87]
	v_and_b32_e32 v87, 0xffff0000, v205
	v_and_b32_e32 v86, 0xffff0000, v209
	v_mov_b32_e32 v32, v89
	v_pk_mul_f32 v[88:89], v[32:33], v[86:87]
	s_waitcnt lgkmcnt(0)
; #define LAS __attribute__((address_space(3)))
; __device__ __forceinline__ float silu_acc(float x) { return x * frcp(1.0f + fexp(-x)); }
; __device__ __forceinline__ void gdn_unit(const Ctx& X, LAS unsigned char* hl, int b, int c, int h, int tid_h, int w4, int lane, int layer) {
;     ...
;             for (int tn = 0; tn < 3; ++tn) {
; #pragma unroll
;                 for (int e = 0; e < 8; ++e) y[tn][e] = 0.f;
; #pragma unroll
;                 for (int k = 0; k < 4; ++k) { float x8[8]; unpack8(*(const LAS u32x4*)(RAW + (tn * 67 + i + k) * 64 + cseg * 8), x8);
;                     y[tn][0] += wq[tn][k][0].x * x8[0]; y[tn][1] += wq[tn][k][0].y * x8[1]; y[tn][2] += wq[tn][k][0].z * x8[2]; y[tn][3] += wq[tn][k][0].w * x8[3];
;                     y[tn][4] += wq[tn][k][1].x * x8[4]; y[tn][5] += wq[tn][k][1].y * x8[5]; y[tn][6] += wq[tn][k][1].z * x8[6]; y[tn][7] += wq[tn][k][1].w * x8[7]; }
; #pragma unroll
;                 for (int e = 0; e < 8; ++e) y[tn][e] = silu_acc(y[tn][e]);
;             }
	v_lshlrev_b32_e32 v203, 16, v214
	v_lshlrev_b32_e32 v202, 16, v210
	v_mov_b32_e32 v86, v22
	v_mov_b32_e32 v87, v26
	v_pk_mul_f32 v[202:203], v[86:87], v[202:203]
	v_mov_b32_e32 v26, v23
	v_add_f32_e32 v22, 0, v202
	v_add_f32_e32 v218, v22, v203
	v_and_b32_e32 v203, 0xffff0000, v214
	v_and_b32_e32 v202, 0xffff0000, v210
	v_pk_mul_f32 v[22:23], v[26:27], v[202:203]
	v_lshlrev_b32_e32 v203, 16, v211
	v_add_f32_e32 v22, 0, v22
	v_add_f32_e32 v214, v22, v23
	v_lshlrev_b32_e32 v202, 16, v215
	v_mov_b32_e32 v22, v28
	v_mov_b32_e32 v23, v24
	v_pk_mul_f32 v[202:203], v[22:23], v[202:203]
	v_and_b32_e32 v210, 0xffff0000, v217
	v_add_f32_e32 v24, 0, v203
	v_add_f32_e32 v219, v202, v24
	v_and_b32_e32 v203, 0xffff0000, v211
	v_and_b32_e32 v202, 0xffff0000, v215
	v_mov_b32_e32 v24, v29
	v_pk_mul_f32 v[28:29], v[24:25], v[202:203]
	v_lshlrev_b32_e32 v203, 16, v216
	v_add_f32_e32 v29, 0, v29
	v_add_f32_e32 v215, v28, v29
	v_lshlrev_b32_e32 v202, 16, v212
	v_mov_b32_e32 v28, v14
	v_mov_b32_e32 v29, v82
	v_pk_mul_f32 v[202:203], v[28:29], v[202:203]
	v_and_b32_e32 v211, 0xffff0000, v213
	v_add_f32_e32 v14, 0, v202
	v_add_f32_e32 v220, v14, v203
	v_and_b32_e32 v203, 0xffff0000, v212
	v_and_b32_e32 v202, 0xffff0000, v216
	v_mov_b32_e32 v14, v83
	v_pk_mul_f32 v[82:83], v[14:15], v[202:203]
	v_lshlrev_b32_e32 v203, 16, v213
	v_add_f32_e32 v83, 0, v83
	v_add_f32_e32 v212, v82, v83
	v_lshlrev_b32_e32 v202, 16, v217
	v_mov_b32_e32 v82, v84
	v_mov_b32_e32 v83, v16
	v_pk_mul_f32 v[202:203], v[82:83], v[202:203]
	s_mov_b32 s4, 0x358637bd
	v_add_f32_e32 v16, 0, v203
	v_add_f32_e32 v216, v202, v16
	ds_read_b128 v[202:205], v156 offset:17408
	ds_read_b128 v[206:209], v156 offset:17536
	v_mov_b32_e32 v16, v85
	v_pk_mul_f32 v[84:85], v[16:17], v[210:211]
	s_waitcnt lgkmcnt(1)
	v_lshlrev_b32_e32 v210, 16, v202
	v_add_f32_e32 v85, 0, v85
	v_add_f32_e32 v213, v84, v85
	s_waitcnt lgkmcnt(0)
	v_lshlrev_b32_e32 v211, 16, v206
	v_mov_b32_e32 v84, v10
	v_mov_b32_e32 v85, v18
	v_pk_mul_f32 v[210:211], v[84:85], v[210:211]
	v_mov_b32_e32 v18, v11
	v_add_f32_e32 v10, v218, v210
	v_add_f32_e32 v217, v10, v211
	v_and_b32_e32 v211, 0xffff0000, v206
	v_and_b32_e32 v210, 0xffff0000, v202
	v_pk_mul_f32 v[10:11], v[18:19], v[210:211]
	v_lshlrev_b32_e32 v211, 16, v203
	v_add_f32_e32 v10, v214, v10
	v_add_f32_e32 v206, v10, v11
	v_lshlrev_b32_e32 v210, 16, v207
	v_mov_b32_e32 v10, v20
	v_mov_b32_e32 v11, v12
	v_pk_mul_f32 v[210:211], v[10:11], v[210:211]
	v_and_b32_e32 v203, 0xffff0000, v203
	v_add_f32_e32 v12, v211, v219
	v_add_f32_e32 v210, v210, v12
	v_and_b32_e32 v202, 0xffff0000, v207
	v_mov_b32_e32 v12, v21
	v_pk_mul_f32 v[20:21], v[12:13], v[202:203]
	v_lshlrev_b32_e32 v203, 16, v208
	v_add_f32_e32 v21, v21, v215
	v_add_f32_e32 v207, v20, v21
	v_lshlrev_b32_e32 v202, 16, v204
	v_mov_b32_e32 v20, v6
	v_mov_b32_e32 v21, v78
	v_pk_mul_f32 v[202:203], v[20:21], v[202:203]
	s_nop 0
	v_add_f32_e32 v6, v220, v202
	v_add_f32_e32 v211, v6, v203
	v_and_b32_e32 v203, 0xffff0000, v204
	v_and_b32_e32 v202, 0xffff0000, v208
	v_mov_b32_e32 v6, v79
	v_pk_mul_f32 v[78:79], v[6:7], v[202:203]
	v_lshlrev_b32_e32 v203, 16, v205
	v_add_f32_e32 v79, v79, v212
	v_add_f32_e32 v204, v78, v79
	v_lshlrev_b32_e32 v202, 16, v209
	v_mov_b32_e32 v78, v80
	v_mov_b32_e32 v79, v8
	v_pk_mul_f32 v[202:203], v[78:79], v[202:203]
	s_nop 0
	v_add_f32_e32 v8, v203, v216
	v_add_f32_e32 v208, v202, v8
	v_mul_f32_e32 v8, 0xbfb8aa3b, v217
	v_and_b32_e32 v203, 0xffff0000, v205
	v_exp_f32_e32 v205, v8
	v_and_b32_e32 v202, 0xffff0000, v209
	v_mov_b32_e32 v8, v81
	v_pk_mul_f32 v[80:81], v[8:9], v[202:203]
	v_mul_f32_e32 v203, 0xbfb8aa3b, v206
	v_exp_f32_e32 v203, v203
	v_add_f32_e32 v81, v81, v213
	v_add_f32_e32 v202, 1.0, v205
	v_add_f32_e32 v205, v80, v81
	v_add_f32_e32 v80, 1.0, v203
	v_mul_f32_e32 v203, 0xbfb8aa3b, v207
	v_mul_f32_e32 v81, 0xbfb8aa3b, v210
	v_exp_f32_e32 v203, v203
	v_exp_f32_e32 v81, v81
	v_mul_f32_e32 v209, 0xbfb8aa3b, v211
	v_rcp_f32_e32 v80, v80
	v_add_f32_e32 v203, 1.0, v203
	v_exp_f32_e32 v209, v209
	v_add_f32_e32 v81, 1.0, v81
	v_rcp_f32_e32 v203, v203
	v_rcp_f32_e32 v81, v81
	v_mul_f32_e32 v206, v206, v80
	v_add_f32_e32 v80, 1.0, v209
	v_mul_f32_e32 v203, v207, v203
	v_rcp_f32_e32 v207, v80
	v_mul_f32_e32 v80, 0xbfb8aa3b, v204
	v_mul_f32_e32 v210, v210, v81
	v_exp_f32_e32 v209, v80
	v_mov_b32_e32 v80, v134
	v_mov_b32_e32 v81, v136
	v_pk_add_f32 v[80:81], v[80:81], 0 op_sel_hi:[1,0]
	v_mov_b32_e32 v136, v135
	v_pk_add_f32 v[80:81], v[80:81], v[136:137]
	v_mov_b32_e32 v136, v168
	v_mov_b32_e32 v137, v170
	v_pk_add_f32 v[136:137], v[136:137], 0 op_sel_hi:[1,0]
	v_mov_b32_e32 v170, v169
	v_mov_b32_e32 v134, v150
	v_mov_b32_e32 v135, v162
	v_mov_b32_e32 v162, v151
	v_pk_add_f32 v[136:137], v[136:137], v[170:171]
	v_mov_b32_e32 v150, v176
	v_mov_b32_e32 v151, v178
	v_pk_add_f32 v[80:81], v[80:81], v[134:135]
	v_pk_add_f32 v[136:137], v[136:137], v[150:151]
	v_mov_b32_e32 v178, v177
	v_pk_add_f32 v[80:81], v[80:81], v[162:163]
	v_pk_add_f32 v[136:137], v[136:137], v[178:179]
	v_mul_f32_e32 v134, 0xbfb8aa3b, v80
	v_mul_f32_e32 v135, 0xbfb8aa3b, v81
	v_mul_f32_e32 v150, 0xbfb8aa3b, v136
	v_mul_f32_e32 v151, 0xbfb8aa3b, v137
	v_exp_f32_e32 v134, v134
	v_exp_f32_e32 v135, v135
	v_exp_f32_e32 v150, v150
	v_exp_f32_e32 v151, v151
	v_add_f32_e32 v134, 1.0, v134
	v_add_f32_e32 v135, 1.0, v135
	v_add_f32_e32 v150, 1.0, v150
	v_add_f32_e32 v151, 1.0, v151
	v_rcp_f32_e32 v134, v134
	v_rcp_f32_e32 v135, v135
	v_rcp_f32_e32 v150, v150
	v_rcp_f32_e32 v151, v151
	v_add_f32_e32 v162, 1.0, v209
	v_pk_mul_f32 v[134:135], v[80:81], v[134:135]
	v_rcp_f32_e32 v168, v162
	v_pk_mul_f32 v[80:81], v[136:137], v[150:151]
; __device__ __forceinline__ float silu_acc(float x) { return x * frcp(1.0f + fexp(-x)); }
; __device__ __forceinline__ void gdn_unit(const Ctx& X, LAS unsigned char* hl, int b, int c, int h, int tid_h, int w4, int lane, int layer) {
;     ...
;                 for (int e = 0; e < 8; ++e) y[tn][e] = silu_acc(y[tn][e]);
;             }
;             float sq = 0.f, sk = 0.f;
; #pragma unroll
;             for (int e = 0; e < 8; ++e) { sq += y[0][e] * y[0][e]; sk += y[1][e] * y[1][e]; }
;             sq += __shfl_xor(sq, 1); sq += __shfl_xor(sq, 2); sq += __shfl_xor(sq, 4);
;             sk += __shfl_xor(sk, 1); sk += __shfl_xor(sk, 2); sk += __shfl_xor(sk, 4);
	v_mov_b32_e32 v136, v121
	v_mov_b32_e32 v137, v119
	v_pk_add_f32 v[136:137], v[136:137], 0 op_sel_hi:[1,0]
	v_mov_b32_e32 v121, v118
	v_pk_add_f32 v[118:119], v[120:121], v[136:137]
	v_mov_b32_e32 v120, v143
	v_mov_b32_e32 v121, v139
	v_pk_add_f32 v[118:119], v[120:121], v[118:119]
	v_mov_b32_e32 v143, v138
	v_pk_add_f32 v[118:119], v[142:143], v[118:119]
	v_mov_b32_e32 v139, v149
	v_mul_f32_e32 v120, 0xbfb8aa3b, v119
	v_exp_f32_e32 v136, v120
	v_mul_f32_e32 v120, 0xbfb8aa3b, v118
	v_exp_f32_e32 v138, v120
	v_mov_b32_e32 v142, v175
	v_add_f32_e32 v136, 1.0, v136
	v_rcp_f32_e32 v137, v136
	v_add_f32_e32 v136, 1.0, v138
	v_mov_b32_e32 v138, v153
	v_pk_add_f32 v[138:139], v[138:139], 0 op_sel_hi:[1,0]
	v_mov_b32_e32 v153, v148
	v_pk_add_f32 v[138:139], v[152:153], v[138:139]
	v_mov_b32_e32 v143, v173
	v_pk_add_f32 v[138:139], v[142:143], v[138:139]
	v_mov_b32_e32 v175, v172
	v_pk_add_f32 v[138:139], v[174:175], v[138:139]
	v_rcp_f32_e32 v136, v136
	v_mul_f32_e32 v142, 0xbfb8aa3b, v139
	v_exp_f32_e32 v142, v142
	v_mul_f32_e32 v143, 0xbfb8aa3b, v138
	v_exp_f32_e32 v143, v143
	v_pk_mul_f32 v[118:119], v[118:119], v[136:137]
	v_add_f32_e32 v136, 1.0, v142
	v_rcp_f32_e32 v137, v136
	v_add_f32_e32 v136, 1.0, v143
	v_pk_mov_b32 v[142:143], v[112:113], v[110:111] op_sel:[1,0]
	v_mov_b32_e32 v113, v111
	v_pk_add_f32 v[142:143], v[142:143], 0 op_sel_hi:[1,0]
	v_rcp_f32_e32 v136, v136
	v_pk_add_f32 v[110:111], v[112:113], v[142:143]
	v_pk_mov_b32 v[112:113], v[126:127], v[122:123] op_sel:[1,0]
	v_mov_b32_e32 v127, v123
	v_pk_add_f32 v[110:111], v[112:113], v[110:111]
	v_mov_b32_e32 v143, v107
	v_pk_add_f32 v[112:113], v[126:127], v[110:111]
	v_pk_mul_f32 v[162:163], v[134:135], v[134:135]
	v_mul_f32_e32 v110, 0xbfb8aa3b, v113
	v_exp_f32_e32 v110, v110
	v_mul_f32_e32 v111, 0xbfb8aa3b, v112
	v_exp_f32_e32 v111, v111
	v_pk_mul_f32 v[120:121], v[80:81], v[80:81]
	v_add_f32_e32 v110, 1.0, v110
	v_rcp_f32_e32 v123, v110
	v_add_f32_e32 v110, 1.0, v111
	v_rcp_f32_e32 v122, v110
	v_pk_mul_f32 v[110:111], v[138:139], v[136:137]
	v_pk_mov_b32 v[138:139], v[166:167], v[164:165] op_sel:[1,0]
	v_mov_b32_e32 v167, v165
	v_pk_mul_f32 v[112:113], v[112:113], v[122:123]
	v_pk_mov_b32 v[122:123], v[144:145], v[140:141] op_sel:[1,0]
	v_mov_b32_e32 v145, v141
	v_pk_add_f32 v[122:123], v[122:123], 0 op_sel_hi:[1,0]
	v_pk_mul_f32 v[126:127], v[118:119], v[118:119]
	v_pk_add_f32 v[122:123], v[144:145], v[122:123]
	v_pk_mul_f32 v[136:137], v[110:111], v[110:111]
	v_pk_add_f32 v[122:123], v[138:139], v[122:123]
	v_rcp_f32_e32 v202, v202
	v_pk_add_f32 v[122:123], v[166:167], v[122:123]
	v_mul_f32_e32 v202, v217, v202
	v_mul_f32_e32 v138, 0xbfb8aa3b, v123
	v_exp_f32_e32 v140, v138
	v_mul_f32_e32 v138, 0xbfb8aa3b, v122
	v_exp_f32_e32 v142, v138
	v_pk_mul_f32 v[138:139], v[112:113], v[112:113]
	v_add_f32_e32 v140, 1.0, v140
	v_rcp_f32_e32 v141, v140
	v_add_f32_e32 v140, 1.0, v142
	v_mov_b32_e32 v142, v109
	v_pk_add_f32 v[142:143], v[142:143], 0 op_sel_hi:[1,0]
	v_mov_b32_e32 v109, v106
	v_pk_add_f32 v[106:107], v[108:109], v[142:143]
	v_mov_b32_e32 v108, v117
	v_mov_b32_e32 v109, v115
	v_pk_add_f32 v[106:107], v[108:109], v[106:107]
	v_mov_b32_e32 v117, v114
	v_pk_add_f32 v[106:107], v[116:117], v[106:107]
	v_rcp_f32_e32 v140, v140
	v_mul_f32_e32 v108, 0xbfb8aa3b, v107
	v_exp_f32_e32 v108, v108
	v_mul_f32_e32 v109, 0xbfb8aa3b, v106
	v_exp_f32_e32 v114, v109
	v_mov_b32_e32 v115, v125
	v_add_f32_e32 v108, 1.0, v108
	v_rcp_f32_e32 v109, v108
	v_add_f32_e32 v108, 1.0, v114
	v_mov_b32_e32 v114, v129
	v_pk_add_f32 v[114:115], v[114:115], 0 op_sel_hi:[1,0]
	v_mov_b32_e32 v129, v124
	v_pk_mul_f32 v[116:117], v[122:123], v[140:141]
	v_pk_add_f32 v[114:115], v[128:129], v[114:115]
	v_mov_b32_e32 v122, v89
	v_mov_b32_e32 v123, v147
	v_pk_add_f32 v[114:115], v[122:123], v[114:115]
	v_mov_b32_e32 v89, v146
	v_pk_add_f32 v[88:89], v[88:89], v[114:115]
	v_rcp_f32_e32 v108, v108
	v_mul_f32_e32 v114, 0xbfb8aa3b, v89
	v_exp_f32_e32 v114, v114
	v_mul_f32_e32 v115, 0xbfb8aa3b, v88
	v_exp_f32_e32 v122, v115
	v_mov_b32_e32 v124, v120
	v_add_f32_e32 v114, 1.0, v114
	v_rcp_f32_e32 v115, v114
	v_add_f32_e32 v114, 1.0, v122
	v_rcp_f32_e32 v114, v114
	v_mov_b32_e32 v125, v162
	v_mov_b32_e32 v162, v121
	v_pk_add_f32 v[120:121], v[124:125], v[162:163]
	v_mov_b32_e32 v124, v137
	v_mov_b32_e32 v125, v127
	v_pk_mul_f32 v[122:123], v[116:117], v[116:117]
	v_pk_add_f32 v[120:121], v[124:125], v[120:121]
	v_mov_b32_e32 v137, v126
	v_pk_mul_f32 v[106:107], v[106:107], v[108:109]
	v_pk_mul_f32 v[88:89], v[88:89], v[114:115]
	v_pk_add_f32 v[120:121], v[136:137], v[120:121]
	v_mov_b32_e32 v124, v123
	v_mov_b32_e32 v125, v139
	v_pk_mul_f32 v[108:109], v[106:107], v[106:107]
	v_pk_mul_f32 v[114:115], v[88:89], v[88:89]
	v_pk_add_f32 v[120:121], v[124:125], v[120:121]
	v_mov_b32_e32 v123, v138
	v_pk_add_f32 v[120:121], v[122:123], v[120:121]
	v_mov_b32_e32 v122, v115
	v_mov_b32_e32 v123, v109
	v_pk_add_f32 v[120:121], v[122:123], v[120:121]
	v_mov_b32_e32 v115, v108
	v_pk_add_f32 v[108:109], v[114:115], v[120:121]
	s_nop 0
	s_nop 0
	v_mul_f32_e32 v120, 0xbfb8aa3b, v208
	v_mul_f32_e32 v121, 0xbfb8aa3b, v205
	v_exp_f32_e32 v120, v120
	v_exp_f32_e32 v121, v121
	s_waitcnt lgkmcnt(0)
	v_add_f32_dpp v108, v108, v108 quad_perm:[1,0,3,2] row_mask:0xf bank_mask:0xf
	v_add_f32_dpp v109, v109, v109 quad_perm:[1,0,3,2] row_mask:0xf bank_mask:0xf
	s_nop 0
	s_nop 0
	v_add_f32_e32 v120, 1.0, v120
	v_add_f32_e32 v121, 1.0, v121
	v_rcp_f32_e32 v120, v120
	v_rcp_f32_e32 v121, v121
	s_waitcnt lgkmcnt(0)
; #define LAS __attribute__((address_space(3)))
; __device__ __forceinline__ bf16_t f2bf(float f) { return (bf16_t)(pk2(f, 0.f) & 0xffffu); }
; __device__ __forceinline__ float fexp(float x) { return __expf(x); }
; __device__ __forceinline__ float silu_acc(float x) { return x * frcp(1.0f + fexp(-x)); }
; __device__ __forceinline__ u32x4 pack8(const float (&f)[8]) { u32x4 w; w.x = pk2(f[0], f[1]); w.y = pk2(f[2], f[3]); w.z = pk2(f[4], f[5]); w.w = pk2(f[6], f[7]); return w; }
; __device__ __forceinline__ void gdn_unit(const Ctx& X, LAS unsigned char* hl, int b, int c, int h, int tid_h, int w4, int lane, int layer) {
;     ...
;                 for (int k = 0; k < 4; ++k) { float x8[8]; unpack8(*(const LAS u32x4*)(RAW + (tn * 67 + i + k) * 64 + cseg * 8), x8);
;                     y[tn][0] += wq[tn][k][0].x * x8[0]; y[tn][1] += wq[tn][k][0].y * x8[1]; y[tn][2] += wq[tn][k][0].z * x8[2]; y[tn][3] += wq[tn][k][0].w * x8[3];
;                     y[tn][4] += wq[tn][k][1].x * x8[4]; y[tn][5] += wq[tn][k][1].y * x8[5]; y[tn][6] += wq[tn][k][1].z * x8[6]; y[tn][7] += wq[tn][k][1].w * x8[7]; }
; #pragma unroll
;                 for (int e = 0; e < 8; ++e) y[tn][e] = silu_acc(y[tn][e]);
;     ...
;             float sq = 0.f, sk = 0.f;
; #pragma unroll
;             for (int e = 0; e < 8; ++e) { sq += y[0][e] * y[0][e]; sk += y[1][e] * y[1][e]; }
;             sq += __shfl_xor(sq, 1); sq += __shfl_xor(sq, 2); sq += __shfl_xor(sq, 4);
;             sk += __shfl_xor(sk, 1); sk += __shfl_xor(sk, 2); sk += __shfl_xor(sk, 4);
;             const float rq = 0.125f * rsqrtf(sq + 1e-6f), rk = rsqrtf(sk + 1e-6f), kd = rk * fexp(G63 - Gi);
;             float t8[8];
; #pragma unroll
;             for (int e = 0; e < 8; ++e) t8[e] = y[0][e] * rq;
;             *(LAS u32x4*)(Q + i * LT + cseg * 8) = pack8(t8);
; #pragma unroll
;             for (int e = 0; e < 8; ++e) t8[e] = y[1][e] * rk;
;             *(LAS u32x4*)(K + i * LT + cseg * 8) = pack8(t8);
; #pragma unroll
;             for (int e = 0; e < 8; ++e) t8[e] = y[1][e] * rk * bi;
;             *(LAS u32x4*)(KB + i * LT + cseg * 8) = pack8(t8);
;             *(LAS u32x4*)(V + i * LT + cseg * 8) = pack8(y[2]);
; #pragma unroll
;             for (int e = 0; e < 8; ++e) KDT[(cseg * 8 + e) * LT + i] = f2bf(y[1][e] * kd);
	v_add_f32_dpp v108, v108, v108 quad_perm:[2,3,0,1] row_mask:0xf bank_mask:0xf
	v_add_f32_dpp v109, v109, v109 quad_perm:[2,3,0,1] row_mask:0xf bank_mask:0xf
	s_nop 0
	s_nop 0
	v_mul_f32_e32 v122, v211, v207
	v_mul_f32_e32 v123, v204, v168
	v_mul_f32_e32 v120, v208, v120
	v_mul_f32_e32 v121, v205, v121
	s_waitcnt lgkmcnt(0)
	v_add_f32_dpp v108, v108, v108 row_half_mirror row_mask:0xf bank_mask:0xf
	v_add_f32_dpp v109, v109, v109 row_half_mirror row_mask:0xf bank_mask:0xf
	v_sub_f32_e32 v115, v194, v201
	v_pk_add_f32 v[108:109], v[108:109], s[4:5] op_sel_hi:[1,0]
	v_mul_f32_e32 v115, 0x3fb8aa3b, v115
	v_mul_f32_e32 v114, 0x4b800000, v109
	v_cmp_gt_f32_e32 vcc, s3, v109
	v_cmp_gt_f32_e64 s[0:1], s3, v108
	v_exp_f32_e32 v124, v115
	v_cndmask_b32_e32 v109, v109, v114, vcc
	v_rsq_f32_e32 v109, v109
	v_mul_f32_e32 v114, 0x4b800000, v108
	v_cndmask_b32_e64 v108, v108, v114, s[0:1]
	v_rsq_f32_e32 v108, v108
	v_mul_f32_e32 v114, 0x45800000, v109
	v_cndmask_b32_e32 v109, v109, v114, vcc
	v_mul_f32_e32 v109, 0x3e000000, v109
	v_mul_f32_e32 v114, 0x45800000, v108
	v_mul_f32_e32 v115, v134, v109
	v_mul_f32_e32 v125, v135, v109
	v_mul_f32_e32 v119, v119, v109
	v_mul_f32_e32 v118, v118, v109
	v_mul_f32_e32 v126, v113, v109
	v_mul_f32_e32 v127, v112, v109
	v_mul_f32_e32 v107, v107, v109
	v_mul_f32_e32 v106, v106, v109
	v_cndmask_b32_e64 v109, v108, v114, s[0:1]
	v_mul_lo_u32 v108, v191, s44
	v_cvt_pk_bf16_f32 v112, v115, v125
	v_cvt_pk_bf16_f32 v113, v119, v118
	v_cvt_pk_bf16_f32 v114, v126, v127
	v_cvt_pk_bf16_f32 v115, v107, v106
	v_add_u32_e32 v106, v193, v108
	ds_write_b128 v106, v[112:115]
	v_mul_f32_e32 v106, v80, v109
	v_mul_f32_e32 v107, v81, v109
	v_mul_f32_e32 v118, v111, v109
	v_mul_f32_e32 v119, v110, v109
	v_mul_f32_e32 v125, v117, v109
	v_mul_f32_e32 v126, v116, v109
	v_mul_f32_e32 v127, v89, v109
	v_mul_f32_e32 v128, v88, v109
	v_cvt_pk_bf16_f32 v112, v106, v107
	v_cvt_pk_bf16_f32 v113, v118, v119
	v_cvt_pk_bf16_f32 v114, v125, v126
	v_cvt_pk_bf16_f32 v115, v127, v128
	v_add_u32_e32 v129, v192, v108
	v_mul_f32_e32 v106, v200, v106
	ds_write_b128 v129, v[112:115]
	v_mul_f32_e32 v107, v200, v107
	v_mul_f32_e32 v113, v200, v118
	v_mul_f32_e32 v114, v200, v119
	v_mul_f32_e32 v115, v200, v125
	v_cvt_pk_bf16_f32 v112, v106, v107
	v_add_u32_e32 v106, v155, v108
	v_mul_f32_e32 v118, v200, v126
	v_mul_f32_e32 v119, v200, v127
	v_mul_f32_e32 v125, v200, v128
	v_mul_f32_e32 v109, v124, v109
	v_cvt_pk_bf16_f32 v113, v113, v114
	v_cvt_pk_bf16_f32 v114, v115, v118
	v_cvt_pk_bf16_f32 v115, v119, v125
	ds_write_b128 v106, v[112:115]
	v_add_u32_e32 v106, v133, v108
	v_cvt_pk_bf16_f32 v112, v202, v206
	v_cvt_pk_bf16_f32 v113, v210, v203
	v_cvt_pk_bf16_f32 v114, v122, v123
	v_cvt_pk_bf16_f32 v115, v120, v121
	ds_write_b128 v106, v[112:115]
	v_lshlrev_b32_e32 v106, 1, v191
	v_mul_f32_e32 v80, v80, v109
	v_mul_u32_u24_e32 v107, 0x90, v190
	v_cvt_pk_bf16_f32 v80, v80, v157
	v_add3_u32 v107, v131, v106, v107
	ds_write_b16 v107, v80
	v_mul_f32_e32 v80, v81, v109
	v_cvt_pk_bf16_f32 v80, v80, v157
	ds_write_b16 v107, v80 offset:144
	v_mul_f32_e32 v80, v111, v109
	v_cvt_pk_bf16_f32 v80, v80, v157
	ds_write_b16 v107, v80 offset:288
	v_mul_f32_e32 v80, v110, v109
	v_cvt_pk_bf16_f32 v80, v80, v157
	ds_write_b16 v107, v80 offset:432
	v_mul_f32_e32 v80, v117, v109
	v_cvt_pk_bf16_f32 v80, v80, v157
	ds_write_b16 v107, v80 offset:576
	v_mul_f32_e32 v80, v116, v109
	v_cvt_pk_bf16_f32 v80, v80, v157
	ds_write_b16 v107, v80 offset:720
	v_mul_f32_e32 v80, v89, v109
	v_cvt_pk_bf16_f32 v80, v80, v157
	ds_write_b16 v107, v80 offset:864
	v_mul_f32_e32 v80, v88, v109
	v_cvt_pk_bf16_f32 v80, v80, v157
	ds_write_b16 v107, v80 offset:1008
	ds_read_b128 v[112:115], v156 offset:4224
	ds_read_b128 v[116:119], v156 offset:4096
	ds_read_b32 v109, v198 offset:128
	ds_read_b32 v110, v199 offset:128
	ds_read_b128 v[120:123], v156 offset:4352
	ds_read_b128 v[124:127], v156 offset:4480
	v_and_b32_e32 v106, 15, v130
	s_waitcnt lgkmcnt(5)
	v_lshlrev_b32_e32 v81, 16, v112
	s_waitcnt lgkmcnt(4)
	v_lshlrev_b32_e32 v80, 16, v116
	v_pk_mul_f32 v[88:89], v[102:103], v[80:81]
	v_and_b32_e32 v81, 0xffff0000, v112
	v_and_b32_e32 v80, 0xffff0000, v116
	v_pk_mul_f32 v[102:103], v[74:75], v[80:81]
	v_lshlrev_b32_e32 v75, 16, v117
	v_lshlrev_b32_e32 v74, 16, v113
	v_pk_mul_f32 v[74:75], v[66:67], v[74:75]
	v_and_b32_e32 v67, 0xffff0000, v117
	v_and_b32_e32 v66, 0xffff0000, v113
	v_pk_mul_f32 v[80:81], v[68:69], v[66:67]
	v_and_b32_e32 v69, 0xffff0000, v118
	v_and_b32_e32 v68, 0xffff0000, v114
	v_pk_mul_f32 v[68:69], v[58:59], v[68:69]
	v_lshlrev_b32_e32 v59, 16, v119
	v_lshlrev_b32_e32 v58, 16, v115
	v_pk_mul_f32 v[58:59], v[76:77], v[58:59]
	v_and_b32_e32 v77, 0xffff0000, v119
	v_and_b32_e32 v76, 0xffff0000, v115
	v_pk_mul_f32 v[60:61], v[60:61], v[76:77]
	s_waitcnt lgkmcnt(0)
	v_lshlrev_b32_e32 v77, 16, v124
	v_lshlrev_b32_e32 v76, 16, v120
	v_lshlrev_b32_e32 v67, 16, v114
	v_lshlrev_b32_e32 v66, 16, v118
	v_pk_mul_f32 v[98:99], v[98:99], v[76:77]
	v_and_b32_e32 v77, 0xffff0000, v124
	v_and_b32_e32 v76, 0xffff0000, v120
	v_pk_mul_f32 v[66:67], v[104:105], v[66:67]
	v_pk_mul_f32 v[104:105], v[70:71], v[76:77]
	v_lshlrev_b32_e32 v71, 16, v121
	v_lshlrev_b32_e32 v70, 16, v125
	ds_read_b128 v[112:115], v156 offset:12672
	ds_read_b128 v[116:119], v156 offset:12800
	v_pk_mul_f32 v[70:71], v[62:63], v[70:71]
	v_and_b32_e32 v63, 0xffff0000, v121
	v_and_b32_e32 v62, 0xffff0000, v125
	v_pk_mul_f32 v[76:77], v[64:65], v[62:63]
	v_and_b32_e32 v65, 0xffff0000, v122
	v_and_b32_e32 v64, 0xffff0000, v126
	v_pk_mul_f32 v[64:65], v[54:55], v[64:65]
	v_lshlrev_b32_e32 v55, 16, v123
	v_lshlrev_b32_e32 v54, 16, v127
	v_pk_mul_f32 v[54:55], v[72:73], v[54:55]
	v_and_b32_e32 v73, 0xffff0000, v123
	v_and_b32_e32 v72, 0xffff0000, v127
	v_pk_mul_f32 v[56:57], v[56:57], v[72:73]
	s_waitcnt lgkmcnt(0)
; #define LAS __attribute__((address_space(3)))
; __device__ __forceinline__ float silu_acc(float x) { return x * frcp(1.0f + fexp(-x)); }
; __device__ __forceinline__ void gdn_unit(const Ctx& X, LAS unsigned char* hl, int b, int c, int h, int tid_h, int w4, int lane, int layer) {
;     ...
;                 for (int k = 0; k < 4; ++k) { float x8[8]; unpack8(*(const LAS u32x4*)(RAW + (tn * 67 + i + k) * 64 + cseg * 8), x8);
;                     y[tn][0] += wq[tn][k][0].x * x8[0]; y[tn][1] += wq[tn][k][0].y * x8[1]; y[tn][2] += wq[tn][k][0].z * x8[2]; y[tn][3] += wq[tn][k][0].w * x8[3];
;                     y[tn][4] += wq[tn][k][1].x * x8[4]; y[tn][5] += wq[tn][k][1].y * x8[5]; y[tn][6] += wq[tn][k][1].z * x8[6]; y[tn][7] += wq[tn][k][1].w * x8[7]; }
; #pragma unroll
;                 for (int e = 0; e < 8; ++e) y[tn][e] = silu_acc(y[tn][e]);
;             }
	v_lshlrev_b32_e32 v73, 16, v116
	v_lshlrev_b32_e32 v72, 16, v112
	v_lshlrev_b32_e32 v63, 16, v126
	v_lshlrev_b32_e32 v62, 16, v122
	v_pk_mul_f32 v[94:95], v[94:95], v[72:73]
	v_and_b32_e32 v73, 0xffff0000, v116
	v_and_b32_e32 v72, 0xffff0000, v112
	v_pk_mul_f32 v[62:63], v[100:101], v[62:63]
	v_pk_mul_f32 v[100:101], v[50:51], v[72:73]
	v_lshlrev_b32_e32 v51, 16, v113
	v_lshlrev_b32_e32 v50, 16, v117
	ds_read_b128 v[120:123], v156 offset:12928
	ds_read_b128 v[124:127], v156 offset:13056
	v_pk_mul_f32 v[50:51], v[46:47], v[50:51]
	v_and_b32_e32 v47, 0xffff0000, v113
	v_and_b32_e32 v46, 0xffff0000, v117
	v_pk_mul_f32 v[72:73], v[48:49], v[46:47]
	v_and_b32_e32 v49, 0xffff0000, v114
	v_and_b32_e32 v48, 0xffff0000, v118
	v_pk_mul_f32 v[48:49], v[38:39], v[48:49]
	v_lshlrev_b32_e32 v39, 16, v115
	v_lshlrev_b32_e32 v38, 16, v119
	v_pk_mul_f32 v[38:39], v[52:53], v[38:39]
	v_and_b32_e32 v53, 0xffff0000, v115
	v_and_b32_e32 v52, 0xffff0000, v119
	v_pk_mul_f32 v[40:41], v[40:41], v[52:53]
	s_waitcnt lgkmcnt(0)
	v_lshlrev_b32_e32 v53, 16, v124
	v_lshlrev_b32_e32 v52, 16, v120
	v_lshlrev_b32_e32 v47, 16, v118
	v_lshlrev_b32_e32 v46, 16, v114
	v_pk_mul_f32 v[90:91], v[90:91], v[52:53]
	v_and_b32_e32 v53, 0xffff0000, v124
	v_and_b32_e32 v52, 0xffff0000, v120
	v_pk_mul_f32 v[46:47], v[96:97], v[46:47]
	v_pk_mul_f32 v[96:97], v[42:43], v[52:53]
	v_lshlrev_b32_e32 v43, 16, v121
	v_lshlrev_b32_e32 v42, 16, v125
	ds_read_b128 v[112:115], v156 offset:21248
	ds_read_b128 v[116:119], v156 offset:21376
	v_pk_mul_f32 v[42:43], v[34:35], v[42:43]
	v_and_b32_e32 v35, 0xffff0000, v121
	v_and_b32_e32 v34, 0xffff0000, v125
	v_pk_mul_f32 v[52:53], v[36:37], v[34:35]
	v_and_b32_e32 v37, 0xffff0000, v122
	v_and_b32_e32 v36, 0xffff0000, v126
	v_pk_mul_f32 v[36:37], v[30:31], v[36:37]
	v_lshlrev_b32_e32 v31, 16, v123
	v_lshlrev_b32_e32 v30, 16, v127
	v_pk_mul_f32 v[30:31], v[44:45], v[30:31]
	v_and_b32_e32 v45, 0xffff0000, v123
	v_and_b32_e32 v44, 0xffff0000, v127
	v_pk_mul_f32 v[32:33], v[32:33], v[44:45]
	s_waitcnt lgkmcnt(0)
	v_lshlrev_b32_e32 v45, 16, v116
	v_lshlrev_b32_e32 v44, 16, v112
	v_pk_mul_f32 v[44:45], v[86:87], v[44:45]
	v_lshlrev_b32_e32 v35, 16, v126
	v_add_f32_e32 v44, 0, v44
	v_add_f32_e32 v86, v44, v45
	v_and_b32_e32 v45, 0xffff0000, v116
	v_and_b32_e32 v44, 0xffff0000, v112
	v_pk_mul_f32 v[26:27], v[26:27], v[44:45]
	v_lshlrev_b32_e32 v34, 16, v122
	v_add_f32_e32 v26, 0, v26
	v_add_f32_e32 v44, v26, v27
	v_lshlrev_b32_e32 v27, 16, v113
	v_lshlrev_b32_e32 v26, 16, v117
	v_pk_mul_f32 v[22:23], v[22:23], v[26:27]
	v_pk_mul_f32 v[34:35], v[92:93], v[34:35]
	v_add_f32_e32 v23, 0, v23
	v_add_f32_e32 v45, v22, v23
	v_and_b32_e32 v23, 0xffff0000, v113
	v_and_b32_e32 v22, 0xffff0000, v117
	v_pk_mul_f32 v[22:23], v[24:25], v[22:23]
	s_nop 0
	v_add_f32_e32 v23, 0, v23
	v_add_f32_e32 v87, v22, v23
	v_lshlrev_b32_e32 v23, 16, v118
	v_lshlrev_b32_e32 v22, 16, v114
	v_pk_mul_f32 v[22:23], v[28:29], v[22:23]
	s_nop 0
	v_add_f32_e32 v22, 0, v22
	v_add_f32_e32 v92, v22, v23
	v_and_b32_e32 v23, 0xffff0000, v114
	v_and_b32_e32 v22, 0xffff0000, v118
	v_pk_mul_f32 v[14:15], v[14:15], v[22:23]
	ds_read_b128 v[22:25], v156 offset:21504
	ds_read_b128 v[26:29], v156 offset:21632
	v_add_f32_e32 v15, 0, v15
	v_add_f32_e32 v93, v14, v15
	v_lshlrev_b32_e32 v15, 16, v115
	v_lshlrev_b32_e32 v14, 16, v119
	v_pk_mul_f32 v[14:15], v[82:83], v[14:15]
	s_nop 0
	v_add_f32_e32 v15, 0, v15
	v_add_f32_e32 v82, v14, v15
	v_and_b32_e32 v15, 0xffff0000, v115
	v_and_b32_e32 v14, 0xffff0000, v119
	v_pk_mul_f32 v[14:15], v[16:17], v[14:15]
	s_nop 0
	v_add_f32_e32 v15, 0, v15
	v_add_f32_e32 v16, v14, v15
	s_waitcnt lgkmcnt(0)
	v_lshlrev_b32_e32 v15, 16, v26
	v_lshlrev_b32_e32 v14, 16, v22
	v_pk_mul_f32 v[14:15], v[84:85], v[14:15]
	s_nop 0
	v_add_f32_e32 v14, v86, v14
	v_add_f32_e32 v17, v14, v15
	v_and_b32_e32 v15, 0xffff0000, v26
	v_and_b32_e32 v14, 0xffff0000, v22
	v_pk_mul_f32 v[14:15], v[18:19], v[14:15]
	v_mov_b32_e32 v19, v51
	v_add_f32_e32 v14, v44, v14
	v_add_f32_e32 v18, v14, v15
	v_lshlrev_b32_e32 v15, 16, v23
	v_lshlrev_b32_e32 v14, 16, v27
	v_pk_mul_f32 v[10:11], v[10:11], v[14:15]
	s_nop 0
	v_add_f32_e32 v11, v11, v45
	v_add_f32_e32 v14, v10, v11
	v_and_b32_e32 v11, 0xffff0000, v23
	v_and_b32_e32 v10, 0xffff0000, v27
	v_pk_mul_f32 v[10:11], v[12:13], v[10:11]
	v_mov_b32_e32 v13, v96
	v_add_f32_e32 v11, v11, v87
	v_add_f32_e32 v12, v10, v11
	v_lshlrev_b32_e32 v11, 16, v28
	v_lshlrev_b32_e32 v10, 16, v24
	v_pk_mul_f32 v[10:11], v[20:21], v[10:11]
	v_mov_b32_e32 v96, v91
	v_add_f32_e32 v10, v92, v10
	v_add_f32_e32 v44, v10, v11
	v_and_b32_e32 v11, 0xffff0000, v24
	v_and_b32_e32 v10, 0xffff0000, v28
	v_pk_mul_f32 v[6:7], v[6:7], v[10:11]
	v_mov_b32_e32 v11, v100
	v_add_f32_e32 v7, v7, v93
	v_add_f32_e32 v45, v6, v7
	v_lshlrev_b32_e32 v7, 16, v25
	v_lshlrev_b32_e32 v6, 16, v29
	v_pk_mul_f32 v[6:7], v[78:79], v[6:7]
	v_mov_b32_e32 v100, v95
	v_add_f32_e32 v7, v7, v82
	v_add_f32_e32 v78, v6, v7
	v_mul_f32_e32 v6, 0xbfb8aa3b, v17
	v_exp_f32_e32 v10, v6
	v_and_b32_e32 v7, 0xffff0000, v25
	v_and_b32_e32 v6, 0xffff0000, v29
	v_pk_mul_f32 v[6:7], v[8:9], v[6:7]
	v_mul_f32_e32 v9, 0xbfb8aa3b, v18
	v_exp_f32_e32 v9, v9
	v_add_f32_e32 v8, 1.0, v10
	v_rcp_f32_e32 v8, v8
	v_add_f32_e32 v7, v7, v16
	v_add_f32_e32 v79, v6, v7
	v_add_f32_e32 v6, 1.0, v9
	v_mul_f32_e32 v9, 0xbfb8aa3b, v44
	v_mul_f32_e32 v7, 0xbfb8aa3b, v14
	v_rcp_f32_e32 v6, v6
	v_exp_f32_e32 v9, v9
	v_exp_f32_e32 v7, v7
	v_mul_f32_e32 v82, v17, v8
	v_mul_f32_e32 v8, 0xbfb8aa3b, v12
	v_exp_f32_e32 v8, v8
	v_mul_f32_e32 v83, v18, v6
	v_add_f32_e32 v6, 1.0, v9
	v_add_f32_e32 v7, 1.0, v7
	v_rcp_f32_e32 v86, v6
	v_mul_f32_e32 v6, 0xbfb8aa3b, v45
; #define LAS __attribute__((address_space(3)))
; __device__ __forceinline__ float fexp(float x) { return __expf(x); }
; __device__ __forceinline__ float silu_acc(float x) { return x * frcp(1.0f + fexp(-x)); }
; __device__ __forceinline__ void gdn_unit(const Ctx& X, LAS unsigned char* hl, int b, int c, int h, int tid_h, int w4, int lane, int layer) {
;     ...
;                 for (int k = 0; k < 4; ++k) { float x8[8]; unpack8(*(const LAS u32x4*)(RAW + (tn * 67 + i + k) * 64 + cseg * 8), x8);
;                     y[tn][0] += wq[tn][k][0].x * x8[0]; y[tn][1] += wq[tn][k][0].y * x8[1]; y[tn][2] += wq[tn][k][0].z * x8[2]; y[tn][3] += wq[tn][k][0].w * x8[3];
;                     y[tn][4] += wq[tn][k][1].x * x8[4]; y[tn][5] += wq[tn][k][1].y * x8[5]; y[tn][6] += wq[tn][k][1].z * x8[6]; y[tn][7] += wq[tn][k][1].w * x8[7]; }
; #pragma unroll
;                 for (int e = 0; e < 8; ++e) y[tn][e] = silu_acc(y[tn][e]);
;             }
;             float sq = 0.f, sk = 0.f;
; #pragma unroll
;             for (int e = 0; e < 8; ++e) { sq += y[0][e] * y[0][e]; sk += y[1][e] * y[1][e]; }
;             sq += __shfl_xor(sq, 1); sq += __shfl_xor(sq, 2); sq += __shfl_xor(sq, 4);
;             sk += __shfl_xor(sk, 1); sk += __shfl_xor(sk, 2); sk += __shfl_xor(sk, 4);
;             const float rq = 0.125f * rsqrtf(sq + 1e-6f), rk = rsqrtf(sk + 1e-6f), kd = rk * fexp(G63 - Gi);
	v_rcp_f32_e32 v7, v7
	v_exp_f32_e32 v10, v6
	v_add_f32_e32 v8, 1.0, v8
	v_rcp_f32_e32 v8, v8
	v_mul_f32_e32 v84, v14, v7
	v_mov_b32_e32 v6, v88
	v_mov_b32_e32 v7, v102
	v_add_f32_e32 v14, 1.0, v10
	v_mov_b32_e32 v10, v94
	v_pk_add_f32 v[6:7], v[6:7], 0 op_sel_hi:[1,0]
	v_mov_b32_e32 v102, v89
	v_pk_add_f32 v[10:11], v[10:11], 0 op_sel_hi:[1,0]
	v_mul_f32_e32 v85, v12, v8
	v_pk_add_f32 v[6:7], v[6:7], v[102:103]
	v_mov_b32_e32 v8, v98
	v_mov_b32_e32 v9, v104
	v_pk_add_f32 v[10:11], v[10:11], v[100:101]
	v_mov_b32_e32 v12, v90
	v_pk_add_f32 v[6:7], v[6:7], v[8:9]
	v_mov_b32_e32 v104, v99
	v_pk_add_f32 v[10:11], v[10:11], v[12:13]
	v_pk_add_f32 v[6:7], v[6:7], v[104:105]
	v_pk_add_f32 v[10:11], v[10:11], v[96:97]
	v_mul_f32_e32 v8, 0xbfb8aa3b, v6
	v_mul_f32_e32 v9, 0xbfb8aa3b, v7
	v_mul_f32_e32 v12, 0xbfb8aa3b, v10
	v_mul_f32_e32 v13, 0xbfb8aa3b, v11
	v_exp_f32_e32 v8, v8
	v_exp_f32_e32 v9, v9
	v_exp_f32_e32 v12, v12
	v_exp_f32_e32 v13, v13
	v_add_f32_e32 v8, 1.0, v8
	v_add_f32_e32 v9, 1.0, v9
	v_add_f32_e32 v12, 1.0, v12
	v_add_f32_e32 v13, 1.0, v13
	v_rcp_f32_e32 v8, v8
	v_rcp_f32_e32 v9, v9
	v_rcp_f32_e32 v12, v12
	v_rcp_f32_e32 v13, v13
	v_mov_b32_e32 v20, v53
	v_pk_mul_f32 v[8:9], v[6:7], v[8:9]
	v_mov_b32_e32 v21, v43
	v_pk_mul_f32 v[6:7], v[10:11], v[12:13]
	v_mov_b32_e32 v10, v81
	v_mov_b32_e32 v11, v75
	v_pk_add_f32 v[10:11], v[10:11], 0 op_sel_hi:[1,0]
	v_mov_b32_e32 v81, v74
	v_pk_add_f32 v[10:11], v[80:81], v[10:11]
	v_mov_b32_e32 v12, v77
	v_mov_b32_e32 v13, v71
	v_pk_add_f32 v[10:11], v[12:13], v[10:11]
	v_mov_b32_e32 v77, v70
	v_pk_add_f32 v[10:11], v[76:77], v[10:11]
	v_mov_b32_e32 v53, v42
	v_mul_f32_e32 v12, 0xbfb8aa3b, v11
	v_exp_f32_e32 v16, v12
	v_mul_f32_e32 v12, 0xbfb8aa3b, v10
	v_exp_f32_e32 v18, v12
	v_pk_mov_b32 v[22:23], v[64:65], v[62:63] op_sel:[1,0]
	v_add_f32_e32 v16, 1.0, v16
	v_rcp_f32_e32 v17, v16
	v_add_f32_e32 v16, 1.0, v18
	v_mov_b32_e32 v18, v73
	v_pk_add_f32 v[18:19], v[18:19], 0 op_sel_hi:[1,0]
	v_mov_b32_e32 v73, v50
	v_pk_add_f32 v[18:19], v[72:73], v[18:19]
	v_rcp_f32_e32 v16, v16
	v_pk_add_f32 v[18:19], v[20:21], v[18:19]
	v_mov_b32_e32 v65, v63
	v_pk_add_f32 v[18:19], v[52:53], v[18:19]
	v_pk_mul_f32 v[10:11], v[10:11], v[16:17]
	v_mul_f32_e32 v20, 0xbfb8aa3b, v19
	v_exp_f32_e32 v20, v20
	v_mul_f32_e32 v21, 0xbfb8aa3b, v18
	v_exp_f32_e32 v21, v21
	v_pk_mov_b32 v[26:27], v[36:37], v[34:35] op_sel:[1,0]
	v_add_f32_e32 v16, 1.0, v20
	v_rcp_f32_e32 v17, v16
	v_add_f32_e32 v16, 1.0, v21
	v_pk_mov_b32 v[20:21], v[68:69], v[66:67] op_sel:[1,0]
	v_mov_b32_e32 v69, v67
	v_pk_add_f32 v[20:21], v[20:21], 0 op_sel_hi:[1,0]
	v_mov_b32_e32 v37, v35
	v_pk_add_f32 v[20:21], v[68:69], v[20:21]
	v_mov_b32_e32 v35, v59
	v_pk_add_f32 v[20:21], v[22:23], v[20:21]
	v_rcp_f32_e32 v16, v16
	v_pk_add_f32 v[20:21], v[64:65], v[20:21]
	v_rcp_f32_e32 v87, v14
	v_mul_f32_e32 v22, 0xbfb8aa3b, v21
	v_exp_f32_e32 v22, v22
	v_mul_f32_e32 v23, 0xbfb8aa3b, v20
	v_exp_f32_e32 v24, v23
	v_pk_mul_f32 v[14:15], v[8:9], v[8:9]
	v_add_f32_e32 v22, 1.0, v22
	v_rcp_f32_e32 v23, v22
	v_add_f32_e32 v22, 1.0, v24
	v_rcp_f32_e32 v22, v22
	v_pk_mul_f32 v[12:13], v[6:7], v[6:7]
	v_pk_mul_f32 v[16:17], v[18:19], v[16:17]
	v_pk_mul_f32 v[24:25], v[10:11], v[10:11]
	v_pk_mul_f32 v[20:21], v[20:21], v[22:23]
	v_pk_mov_b32 v[22:23], v[48:49], v[46:47] op_sel:[1,0]
	v_mov_b32_e32 v49, v47
	v_pk_add_f32 v[22:23], v[22:23], 0 op_sel_hi:[1,0]
	v_pk_mul_f32 v[18:19], v[16:17], v[16:17]
	v_pk_add_f32 v[22:23], v[48:49], v[22:23]
	v_ashrrev_i32_e32 v72, 4, v130
	v_pk_add_f32 v[22:23], v[26:27], v[22:23]
	v_lshlrev_b32_e32 v77, 2, v72
	v_pk_add_f32 v[22:23], v[36:37], v[22:23]
	v_mov_b32_e32 v36, v57
	v_mul_f32_e32 v26, 0xbfb8aa3b, v23
	v_exp_f32_e32 v28, v26
	v_mul_f32_e32 v26, 0xbfb8aa3b, v22
	v_exp_f32_e32 v34, v26
	v_mov_b32_e32 v37, v55
	v_add_f32_e32 v28, 1.0, v28
	v_rcp_f32_e32 v29, v28
	v_add_f32_e32 v28, 1.0, v34
	v_mov_b32_e32 v34, v61
	v_pk_add_f32 v[34:35], v[34:35], 0 op_sel_hi:[1,0]
	v_mov_b32_e32 v61, v58
	v_pk_add_f32 v[34:35], v[60:61], v[34:35]
	v_mov_b32_e32 v57, v54
	v_pk_add_f32 v[34:35], v[36:37], v[34:35]
	v_rcp_f32_e32 v28, v28
	v_pk_add_f32 v[34:35], v[56:57], v[34:35]
	v_pk_mul_f32 v[26:27], v[20:21], v[20:21]
	v_mul_f32_e32 v36, 0xbfb8aa3b, v35
	v_exp_f32_e32 v36, v36
	v_mul_f32_e32 v37, 0xbfb8aa3b, v34
	v_exp_f32_e32 v37, v37
	v_pk_mul_f32 v[22:23], v[22:23], v[28:29]
	v_add_f32_e32 v28, 1.0, v36
	v_rcp_f32_e32 v29, v28
	v_add_f32_e32 v28, 1.0, v37
	v_mov_b32_e32 v36, v41
	v_mov_b32_e32 v37, v39
	v_pk_add_f32 v[36:37], v[36:37], 0 op_sel_hi:[1,0]
	v_mov_b32_e32 v41, v38
	v_pk_add_f32 v[36:37], v[40:41], v[36:37]
	v_mov_b32_e32 v38, v33
	v_mov_b32_e32 v39, v31
	v_pk_add_f32 v[36:37], v[38:39], v[36:37]
	v_mov_b32_e32 v33, v30
	v_pk_add_f32 v[30:31], v[32:33], v[36:37]
	v_rcp_f32_e32 v28, v28
	v_mul_f32_e32 v32, 0xbfb8aa3b, v31
	v_exp_f32_e32 v32, v32
	v_mul_f32_e32 v33, 0xbfb8aa3b, v30
	v_exp_f32_e32 v36, v33
	v_mov_b32_e32 v38, v12
	v_add_f32_e32 v32, 1.0, v32
	v_rcp_f32_e32 v33, v32
	v_add_f32_e32 v32, 1.0, v36
	v_rcp_f32_e32 v32, v32
	v_mov_b32_e32 v39, v14
	v_mov_b32_e32 v14, v13
	v_pk_add_f32 v[12:13], v[38:39], v[14:15]
	v_mov_b32_e32 v14, v19
	v_mov_b32_e32 v15, v25
	v_pk_mul_f32 v[36:37], v[22:23], v[22:23]
	v_pk_add_f32 v[12:13], v[14:15], v[12:13]
	v_mov_b32_e32 v19, v24
	v_pk_mul_f32 v[28:29], v[34:35], v[28:29]
	v_pk_mul_f32 v[30:31], v[30:31], v[32:33]
	v_pk_add_f32 v[12:13], v[18:19], v[12:13]
	v_mov_b32_e32 v14, v37
	v_mov_b32_e32 v15, v27
	v_pk_mul_f32 v[34:35], v[28:29], v[28:29]
	v_pk_mul_f32 v[32:33], v[30:31], v[30:31]
	v_pk_add_f32 v[12:13], v[14:15], v[12:13]
	v_mov_b32_e32 v37, v26
	v_pk_add_f32 v[12:13], v[36:37], v[12:13]
	v_mov_b32_e32 v14, v33
	v_mov_b32_e32 v15, v35
	v_pk_add_f32 v[12:13], v[14:15], v[12:13]
	v_mov_b32_e32 v33, v34
	v_pk_add_f32 v[12:13], v[32:33], v[12:13]
	s_nop 0
	s_nop 0
	v_mul_f32_e32 v18, 0xbfb8aa3b, v78
	v_mul_f32_e32 v19, 0xbfb8aa3b, v79
	v_exp_f32_e32 v18, v18
	v_exp_f32_e32 v19, v19
	s_waitcnt lgkmcnt(0)
; #define LAS __attribute__((address_space(3)))
; __device__ __forceinline__ bf16_t f2bf(float f) { return (bf16_t)(pk2(f, 0.f) & 0xffffu); }
; __device__ __forceinline__ float fexp(float x) { return __expf(x); }
; __device__ __forceinline__ u32x4 pack8(const float (&f)[8]) { u32x4 w; w.x = pk2(f[0], f[1]); w.y = pk2(f[2], f[3]); w.z = pk2(f[4], f[5]); w.w = pk2(f[6], f[7]); return w; }
; #define LBAR() do { asm volatile("s_waitcnt lgkmcnt(0)" ::: "memory"); __builtin_amdgcn_s_barrier(); asm volatile("" ::: "memory"); } while (0)
; __device__ __forceinline__ void gdn_unit(const Ctx& X, LAS unsigned char* hl, int b, int c, int h, int tid_h, int w4, int lane, int layer) {
;     ...
;             sq += __shfl_xor(sq, 1); sq += __shfl_xor(sq, 2); sq += __shfl_xor(sq, 4);
;             sk += __shfl_xor(sk, 1); sk += __shfl_xor(sk, 2); sk += __shfl_xor(sk, 4);
;             const float rq = 0.125f * rsqrtf(sq + 1e-6f), rk = rsqrtf(sk + 1e-6f), kd = rk * fexp(G63 - Gi);
;             float t8[8];
; #pragma unroll
;             for (int e = 0; e < 8; ++e) t8[e] = y[0][e] * rq;
;             *(LAS u32x4*)(Q + i * LT + cseg * 8) = pack8(t8);
; #pragma unroll
;             for (int e = 0; e < 8; ++e) t8[e] = y[1][e] * rk;
;             *(LAS u32x4*)(K + i * LT + cseg * 8) = pack8(t8);
; #pragma unroll
;             for (int e = 0; e < 8; ++e) t8[e] = y[1][e] * rk * bi;
;             *(LAS u32x4*)(KB + i * LT + cseg * 8) = pack8(t8);
;             *(LAS u32x4*)(V + i * LT + cseg * 8) = pack8(y[2]);
; #pragma unroll
;             for (int e = 0; e < 8; ++e) KDT[(cseg * 8 + e) * LT + i] = f2bf(y[1][e] * kd);
;         }
;     }
;     LBAR();
;     }
;     {
;         f32x4 aA[4], aP[4];
; #pragma unroll
;         for (int ct = 0; ct < 4; ++ct) { aA[ct] = mma16(KB, 16 * w4, K, 16 * ct, (f32x4){0.f, 0.f, 0.f, 0.f}, r, q); aP[ct] = mma16(Q, 16 * w4, K, 16 * ct, (f32x4){0.f, 0.f, 0.f, 0.f}, r, q); }
	v_add_f32_dpp v12, v12, v12 quad_perm:[1,0,3,2] row_mask:0xf bank_mask:0xf
	v_add_f32_dpp v13, v13, v13 quad_perm:[1,0,3,2] row_mask:0xf bank_mask:0xf
	s_nop 0
	s_nop 0
	v_add_f32_e32 v18, 1.0, v18
	v_add_f32_e32 v19, 1.0, v19
	v_rcp_f32_e32 v18, v18
	v_rcp_f32_e32 v19, v19
	s_waitcnt lgkmcnt(0)
	v_add_f32_dpp v12, v12, v12 quad_perm:[2,3,0,1] row_mask:0xf bank_mask:0xf
	v_add_f32_dpp v13, v13, v13 quad_perm:[2,3,0,1] row_mask:0xf bank_mask:0xf
	s_nop 0
	s_nop 0
	v_mul_f32_e32 v24, v44, v86
	v_mul_f32_e32 v25, v45, v87
	v_mul_f32_e32 v18, v78, v18
	v_mul_f32_e32 v19, v79, v19
	s_waitcnt lgkmcnt(0)
	v_add_f32_dpp v12, v12, v12 row_half_mirror row_mask:0xf bank_mask:0xf
	v_add_f32_dpp v13, v13, v13 row_half_mirror row_mask:0xf bank_mask:0xf
	v_sub_f32_e32 v15, v194, v110
	v_pk_add_f32 v[12:13], v[12:13], s[4:5] op_sel_hi:[1,0]
	v_mul_f32_e32 v15, 0x3fb8aa3b, v15
	v_mul_f32_e32 v14, 0x4b800000, v13
	v_cmp_gt_f32_e32 vcc, s3, v13
	v_cmp_gt_f32_e64 s[0:1], s3, v12
	v_exp_f32_e32 v15, v15
	v_cndmask_b32_e32 v13, v13, v14, vcc
	v_rsq_f32_e32 v13, v13
	v_mul_f32_e32 v14, 0x4b800000, v12
	v_cndmask_b32_e64 v12, v12, v14, s[0:1]
	v_rsq_f32_e32 v12, v12
	v_mul_f32_e32 v14, 0x45800000, v13
	v_cndmask_b32_e32 v13, v13, v14, vcc
	v_mul_f32_e32 v13, 0x3e000000, v13
	v_mul_f32_e32 v8, v8, v13
	v_mul_f32_e32 v9, v9, v13
	v_mul_f32_e32 v11, v11, v13
	v_mul_f32_e32 v10, v10, v13
	v_mul_f32_e32 v21, v21, v13
	v_mul_f32_e32 v20, v20, v13
	v_mul_f32_e32 v26, v29, v13
	v_mul_f32_e32 v13, v28, v13
	v_mul_f32_e32 v14, 0x45800000, v12
	v_cvt_pk_bf16_f32 v8, v8, v9
	v_cvt_pk_bf16_f32 v9, v11, v10
	v_cvt_pk_bf16_f32 v10, v21, v20
	v_cvt_pk_bf16_f32 v11, v26, v13
	v_add_u32_e32 v13, 0x1200, v108
	v_cndmask_b32_e64 v12, v12, v14, s[0:1]
	v_add_u32_e32 v14, v193, v13
	ds_write_b128 v14, v[8:11]
	v_mul_f32_e32 v14, v6, v12
	v_mul_f32_e32 v20, v7, v12
	v_mul_f32_e32 v21, v17, v12
	v_mul_f32_e32 v26, v16, v12
	v_mul_f32_e32 v27, v23, v12
	v_mul_f32_e32 v28, v22, v12
	v_mul_f32_e32 v29, v31, v12
	v_mul_f32_e32 v32, v30, v12
	v_cvt_pk_bf16_f32 v8, v14, v20
	v_cvt_pk_bf16_f32 v9, v21, v26
	v_cvt_pk_bf16_f32 v10, v27, v28
	v_cvt_pk_bf16_f32 v11, v29, v32
	v_add_u32_e32 v33, v192, v13
	ds_write_b128 v33, v[8:11]
	v_mul_f32_e32 v8, v109, v14
	v_mul_f32_e32 v9, v109, v20
	v_mul_f32_e32 v10, v109, v21
	v_mul_f32_e32 v11, v109, v26
	v_mul_f32_e32 v14, v109, v27
	v_mul_f32_e32 v12, v15, v12
	v_mul_f32_e32 v20, v109, v28
	v_mul_f32_e32 v21, v109, v29
	v_mul_f32_e32 v26, v109, v32
	v_cvt_pk_bf16_f32 v8, v8, v9
	v_cvt_pk_bf16_f32 v9, v10, v11
	v_cvt_pk_bf16_f32 v10, v14, v20
	v_cvt_pk_bf16_f32 v11, v21, v26
	v_add_u32_e32 v14, v155, v13
	v_add_u32_e32 v13, v133, v13
	v_mul_f32_e32 v6, v6, v12
	ds_write_b128 v14, v[8:11]
	v_cvt_pk_bf16_f32 v8, v82, v83
	v_cvt_pk_bf16_f32 v9, v84, v85
	v_cvt_pk_bf16_f32 v10, v24, v25
	v_cvt_pk_bf16_f32 v11, v18, v19
	ds_write_b128 v13, v[8:11]
	v_cvt_pk_bf16_f32 v6, v6, v157
	ds_write_b16 v107, v6 offset:64
	v_mul_f32_e32 v6, v7, v12
	v_cvt_pk_bf16_f32 v6, v6, v157
	ds_write_b16 v107, v6 offset:208
	v_mul_f32_e32 v6, v17, v12
	v_cvt_pk_bf16_f32 v6, v6, v157
	ds_write_b16 v107, v6 offset:352
	v_mul_f32_e32 v6, v16, v12
	v_cvt_pk_bf16_f32 v6, v6, v157
	ds_write_b16 v107, v6 offset:496
	v_mul_f32_e32 v6, v23, v12
	v_cvt_pk_bf16_f32 v6, v6, v157
	ds_write_b16 v107, v6 offset:640
	v_mul_f32_e32 v6, v22, v12
	v_cvt_pk_bf16_f32 v6, v6, v157
	ds_write_b16 v107, v6 offset:784
	v_mul_f32_e32 v6, v31, v12
	v_cvt_pk_bf16_f32 v6, v6, v157
	ds_write_b16 v107, v6 offset:928
	v_mul_f32_e32 v6, v30, v12
	v_cvt_pk_bf16_f32 v6, v6, v157
	ds_write_b16 v107, v6 offset:1072
	v_or_b32_e32 v6, s39, v106
	v_mul_u32_u24_e32 v78, 0x90, v6
	v_and_b32_e32 v14, -16, v130
	v_mul_u32_u24_e32 v82, 0x90, v106
	s_waitcnt lgkmcnt(0)
	s_barrier
	v_bfe_u32 v6, v224, 6, 2
	v_and_b32_e32 v7, 15, v232
	v_lshrrev_b32_e32 v8, 4, v232
	v_lshl_or_b32 v9, v6, 4, v7
	v_mul_u32_u24_e32 v10, 0x90, v9
	v_mul_u32_u24_e32 v11, 0x90, v7
	v_lshl_add_u32 v13, v8, 4, v10
	v_lshl_add_u32 v11, v8, 4, v11
	v_add_u32_e32 v13, v182, v13
	v_add_u32_e32 v11, v182, v11
	v_add_u32_e32 v15, 0x4800, v13
	v_add_u32_e32 v11, 0x2400, v11
	ds_read_b128 v[16:19], v15
	ds_read_b128 v[20:23], v15 offset:64
	ds_read_b128 v[24:27], v13
	ds_read_b128 v[28:31], v13 offset:64
	ds_read_b128 v[32:35], v11
	ds_read_b128 v[36:39], v11 offset:64
	ds_read_b128 v[40:43], v11 offset:2304
	ds_read_b128 v[44:47], v11 offset:2368
	ds_read_b128 v[48:51], v11 offset:4608
	ds_read_b128 v[52:55], v11 offset:4672
	ds_read_b128 v[56:59], v11 offset:6912
	ds_read_b128 v[60:63], v11 offset:6976
	v_lshl_add_u32 v66, v9, 2, v185
	v_lshl_add_u32 v67, v8, 4, v185
	ds_read_b32 v64, v66
	ds_read_b128 v[136:139], v67
	ds_read_b128 v[140:143], v67 offset:64
	v_lshlrev_b32_e32 v12, 2, v8
	v_sub_u32_e32 v12, v9, v12
	v_lshl_add_u32 v65, v8, 3, v10
	v_add_u32_e32 v68, v186, v65
	v_add_u32_e32 v69, v184, v65
	s_waitcnt lgkmcnt(3)
	v_mfma_f32_16x16x32_bf16 v[190:193], v[32:35], v[16:19], 0
	v_mfma_f32_16x16x32_bf16 v[206:209], v[32:35], v[24:27], 0
	v_mfma_f32_16x16x32_bf16 v[194:197], v[40:43], v[16:19], 0
	v_mfma_f32_16x16x32_bf16 v[210:213], v[40:43], v[24:27], 0
	v_mfma_f32_16x16x32_bf16 v[198:201], v[48:51], v[16:19], 0
	v_mfma_f32_16x16x32_bf16 v[214:217], v[48:51], v[24:27], 0
	v_mfma_f32_16x16x32_bf16 v[202:205], v[56:59], v[16:19], 0
	v_mfma_f32_16x16x32_bf16 v[218:221], v[56:59], v[24:27], 0
	ds_read_b128 v[144:147], v67 offset:128
	ds_read_b128 v[148:151], v67 offset:192
	v_mfma_f32_16x16x32_bf16 v[190:193], v[36:39], v[20:23], v[190:193]
	v_mfma_f32_16x16x32_bf16 v[206:209], v[36:39], v[28:31], v[206:209]
	v_mfma_f32_16x16x32_bf16 v[194:197], v[44:47], v[20:23], v[194:197]
	v_mfma_f32_16x16x32_bf16 v[210:213], v[44:47], v[28:31], v[210:213]
	v_mfma_f32_16x16x32_bf16 v[198:201], v[52:55], v[20:23], v[198:201]
	v_mfma_f32_16x16x32_bf16 v[214:217], v[52:55], v[28:31], v[214:217]
	v_mfma_f32_16x16x32_bf16 v[202:205], v[60:63], v[20:23], v[202:205]
	v_mfma_f32_16x16x32_bf16 v[218:221], v[60:63], v[28:31], v[218:221]
	v_readlane_b32 s0, v252, 48
	v_readlane_b32 s1, v252, 49
	s_waitcnt lgkmcnt(0)
; __device__ __forceinline__ bf16_t f2bf(float f) { return (bf16_t)(pk2(f, 0.f) & 0xffffu); }
; __device__ __forceinline__ float fexp(float x) { return __expf(x); }
; #define LBAR() do { asm volatile("s_waitcnt lgkmcnt(0)" ::: "memory"); __builtin_amdgcn_s_barrier(); asm volatile("" ::: "memory"); } while (0)
; __device__ __forceinline__ void gdn_unit(const Ctx& X, LAS unsigned char* hl, int b, int c, int h, int tid_h, int w4, int lane, int layer) {
;     ...
; #pragma unroll
;         for (int ct = 0; ct < 4; ++ct)
; #pragma unroll
;             for (int j = 0; j < 4; ++j) { const int ii = 16 * w4 + 4 * q + j, col = 16 * ct + r;
;                 const float L = fexp(fminf(Gs[ii] - Gs[col], 0.f));
;                 AB[ii * LT + col] = f2bf(ii > col ? aA[ct][j] * L : 0.f);
;                 P[ii * LT + col] = f2bf(ii >= col ? aP[ct][j] * L : 0.f); }
;     }
;     LBAR();
	v_sub_f32_e32 v70, v64, v136
	v_sub_f32_e32 v71, v64, v137
	v_sub_f32_e32 v73, v64, v138
	v_sub_f32_e32 v74, v64, v139
	v_min_f32_e32 v70, 0, v70
	v_min_f32_e32 v71, 0, v71
	v_min_f32_e32 v73, 0, v73
	v_min_f32_e32 v74, 0, v74
	v_mul_f32_e32 v70, 0x3fb8aa3b, v70
	v_mul_f32_e32 v71, 0x3fb8aa3b, v71
	v_mul_f32_e32 v73, 0x3fb8aa3b, v73
	v_mul_f32_e32 v74, 0x3fb8aa3b, v74
	v_exp_f32_e32 v70, v70
	v_exp_f32_e32 v71, v71
	v_exp_f32_e32 v73, v73
	v_exp_f32_e32 v74, v74
	v_cmp_lt_i32_e32 vcc, 0, v12
	v_cmp_lt_i32_e64 s[4:5], 1, v12
	v_cmp_lt_i32_e64 s[6:7], 2, v12
	v_cmp_lt_i32_e64 s[24:25], 3, v12
	v_mul_f32_e32 v75, v190, v70
	v_mul_f32_e32 v76, v191, v71
	v_mul_f32_e32 v79, v192, v73
	v_mul_f32_e32 v80, v193, v74
	v_mul_f32_e32 v81, v206, v70
	v_mul_f32_e32 v83, v207, v71
	v_mul_f32_e32 v84, v208, v73
	v_mul_f32_e32 v114, v209, v74
	v_cndmask_b32_e32 v75, 0, v75, vcc
	v_cndmask_b32_e64 v76, 0, v76, s[4:5]
	v_cndmask_b32_e64 v79, 0, v79, s[6:7]
	v_cndmask_b32_e64 v80, 0, v80, s[24:25]
	v_cmp_le_i32_e32 vcc, 0, v12
	v_cmp_le_i32_e64 s[4:5], 1, v12
	v_cmp_le_i32_e64 s[6:7], 2, v12
	v_cmp_le_i32_e64 s[24:25], 3, v12
	v_cvt_pk_bf16_f32 v116, v75, v76
	v_cvt_pk_bf16_f32 v117, v79, v80
	ds_write_b64 v68, v[116:117]
	v_cndmask_b32_e32 v81, 0, v81, vcc
	v_cndmask_b32_e64 v83, 0, v83, s[4:5]
	v_cndmask_b32_e64 v84, 0, v84, s[6:7]
	v_cndmask_b32_e64 v114, 0, v114, s[24:25]
	v_cvt_pk_bf16_f32 v152, v81, v83
	v_cvt_pk_bf16_f32 v153, v84, v114
	ds_write_b64 v69, v[152:153]
	v_sub_f32_e32 v70, v64, v140
	v_sub_f32_e32 v71, v64, v141
	v_sub_f32_e32 v73, v64, v142
	v_sub_f32_e32 v74, v64, v143
	v_min_f32_e32 v70, 0, v70
	v_min_f32_e32 v71, 0, v71
	v_min_f32_e32 v73, 0, v73
	v_min_f32_e32 v74, 0, v74
	v_mul_f32_e32 v70, 0x3fb8aa3b, v70
	v_mul_f32_e32 v71, 0x3fb8aa3b, v71
	v_mul_f32_e32 v73, 0x3fb8aa3b, v73
	v_mul_f32_e32 v74, 0x3fb8aa3b, v74
	v_exp_f32_e32 v70, v70
	v_exp_f32_e32 v71, v71
	v_exp_f32_e32 v73, v73
	v_exp_f32_e32 v74, v74
	v_cmp_lt_i32_e32 vcc, 16, v12
	v_cmp_lt_i32_e64 s[4:5], 17, v12
	v_cmp_lt_i32_e64 s[6:7], 18, v12
	v_cmp_lt_i32_e64 s[24:25], 19, v12
	v_mul_f32_e32 v75, v194, v70
	v_mul_f32_e32 v76, v195, v71
	v_mul_f32_e32 v79, v196, v73
	v_mul_f32_e32 v80, v197, v74
	v_mul_f32_e32 v81, v210, v70
	v_mul_f32_e32 v83, v211, v71
	v_mul_f32_e32 v84, v212, v73
	v_mul_f32_e32 v114, v213, v74
	v_cndmask_b32_e32 v75, 0, v75, vcc
	v_cndmask_b32_e64 v76, 0, v76, s[4:5]
	v_cndmask_b32_e64 v79, 0, v79, s[6:7]
	v_cndmask_b32_e64 v80, 0, v80, s[24:25]
	v_cmp_le_i32_e32 vcc, 16, v12
	v_cmp_le_i32_e64 s[4:5], 17, v12
	v_cmp_le_i32_e64 s[6:7], 18, v12
	v_cmp_le_i32_e64 s[24:25], 19, v12
	v_cvt_pk_bf16_f32 v116, v75, v76
	v_cvt_pk_bf16_f32 v117, v79, v80
	ds_write_b64 v68, v[116:117] offset:32
	v_cndmask_b32_e32 v81, 0, v81, vcc
	v_cndmask_b32_e64 v83, 0, v83, s[4:5]
	v_cndmask_b32_e64 v84, 0, v84, s[6:7]
	v_cndmask_b32_e64 v114, 0, v114, s[24:25]
	v_cvt_pk_bf16_f32 v152, v81, v83
	v_cvt_pk_bf16_f32 v153, v84, v114
	ds_write_b64 v69, v[152:153] offset:32
	v_sub_f32_e32 v70, v64, v144
	v_sub_f32_e32 v71, v64, v145
	v_sub_f32_e32 v73, v64, v146
	v_sub_f32_e32 v74, v64, v147
	v_min_f32_e32 v70, 0, v70
	v_min_f32_e32 v71, 0, v71
	v_min_f32_e32 v73, 0, v73
	v_min_f32_e32 v74, 0, v74
	v_mul_f32_e32 v70, 0x3fb8aa3b, v70
	v_mul_f32_e32 v71, 0x3fb8aa3b, v71
	v_mul_f32_e32 v73, 0x3fb8aa3b, v73
	v_mul_f32_e32 v74, 0x3fb8aa3b, v74
	v_exp_f32_e32 v70, v70
	v_exp_f32_e32 v71, v71
	v_exp_f32_e32 v73, v73
	v_exp_f32_e32 v74, v74
	v_cmp_lt_i32_e32 vcc, 32, v12
	v_cmp_lt_i32_e64 s[4:5], 33, v12
	v_cmp_lt_i32_e64 s[6:7], 34, v12
	v_cmp_lt_i32_e64 s[24:25], 35, v12
	v_mul_f32_e32 v75, v198, v70
	v_mul_f32_e32 v76, v199, v71
	v_mul_f32_e32 v79, v200, v73
	v_mul_f32_e32 v80, v201, v74
	v_mul_f32_e32 v81, v214, v70
	v_mul_f32_e32 v83, v215, v71
	v_mul_f32_e32 v84, v216, v73
	v_mul_f32_e32 v114, v217, v74
	v_cndmask_b32_e32 v75, 0, v75, vcc
	v_cndmask_b32_e64 v76, 0, v76, s[4:5]
	v_cndmask_b32_e64 v79, 0, v79, s[6:7]
	v_cndmask_b32_e64 v80, 0, v80, s[24:25]
	v_cmp_le_i32_e32 vcc, 32, v12
	v_cmp_le_i32_e64 s[4:5], 33, v12
	v_cmp_le_i32_e64 s[6:7], 34, v12
	v_cmp_le_i32_e64 s[24:25], 35, v12
	v_cvt_pk_bf16_f32 v116, v75, v76
	v_cvt_pk_bf16_f32 v117, v79, v80
	ds_write_b64 v68, v[116:117] offset:64
	v_cndmask_b32_e32 v81, 0, v81, vcc
	v_cndmask_b32_e64 v83, 0, v83, s[4:5]
	v_cndmask_b32_e64 v84, 0, v84, s[6:7]
	v_cndmask_b32_e64 v114, 0, v114, s[24:25]
	v_cvt_pk_bf16_f32 v152, v81, v83
	v_cvt_pk_bf16_f32 v153, v84, v114
	ds_write_b64 v69, v[152:153] offset:64
	v_sub_f32_e32 v70, v64, v148
	v_sub_f32_e32 v71, v64, v149
	v_sub_f32_e32 v73, v64, v150
	v_sub_f32_e32 v74, v64, v151
	v_min_f32_e32 v70, 0, v70
	v_min_f32_e32 v71, 0, v71
	v_min_f32_e32 v73, 0, v73
	v_min_f32_e32 v74, 0, v74
	v_mul_f32_e32 v70, 0x3fb8aa3b, v70
	v_mul_f32_e32 v71, 0x3fb8aa3b, v71
	v_mul_f32_e32 v73, 0x3fb8aa3b, v73
	v_mul_f32_e32 v74, 0x3fb8aa3b, v74
	v_exp_f32_e32 v70, v70
	v_exp_f32_e32 v71, v71
	v_exp_f32_e32 v73, v73
	v_exp_f32_e32 v74, v74
	v_cmp_lt_i32_e32 vcc, 48, v12
	v_cmp_lt_i32_e64 s[4:5], 49, v12
	v_cmp_lt_i32_e64 s[6:7], 50, v12
	v_cmp_lt_i32_e64 s[24:25], 51, v12
	v_mul_f32_e32 v75, v202, v70
	v_mul_f32_e32 v76, v203, v71
	v_mul_f32_e32 v79, v204, v73
	v_mul_f32_e32 v80, v205, v74
	v_mul_f32_e32 v81, v218, v70
	v_mul_f32_e32 v83, v219, v71
	v_mul_f32_e32 v84, v220, v73
	v_mul_f32_e32 v114, v221, v74
	v_cndmask_b32_e32 v75, 0, v75, vcc
	v_cndmask_b32_e64 v76, 0, v76, s[4:5]
	v_cndmask_b32_e64 v79, 0, v79, s[6:7]
	v_cndmask_b32_e64 v80, 0, v80, s[24:25]
	v_cmp_le_i32_e32 vcc, 48, v12
	v_cmp_le_i32_e64 s[4:5], 49, v12
	v_cmp_le_i32_e64 s[6:7], 50, v12
	v_cmp_le_i32_e64 s[24:25], 51, v12
	v_cvt_pk_bf16_f32 v116, v75, v76
	v_cvt_pk_bf16_f32 v117, v79, v80
	ds_write_b64 v68, v[116:117] offset:96
	v_cndmask_b32_e32 v81, 0, v81, vcc
	v_cndmask_b32_e64 v83, 0, v83, s[4:5]
	v_cndmask_b32_e64 v84, 0, v84, s[6:7]
	v_cndmask_b32_e64 v114, 0, v114, s[24:25]
	v_cvt_pk_bf16_f32 v152, v81, v83
	v_cvt_pk_bf16_f32 v153, v84, v114
	ds_write_b64 v69, v[152:153] offset:96
	s_waitcnt lgkmcnt(0)
	s_barrier
; #define LAS __attribute__((address_space(3)))
; __device__ __forceinline__ float bf2f(bf16_t b) { return __uint_as_float((unsigned)b << 16); }
; __device__ __forceinline__ float fexp(float x) { return __expf(x); }
; __device__ __forceinline__ void gdn_unit(const Ctx& X, LAS unsigned char* hl, int b, int c, int h, int tid_h, int w4, int lane, int layer) {
;     ...
;     if (w4 < 2) {
;         const int col = tid_h & 63; const LAS bf16_t* src = w4 == 0 ? V : KB;
; #pragma unroll
;         for (int i = 0; i < 64; ++i) { const float sc = w4 == 0 ? Bs[i] : fexp(Gs[i]); rc[i] = bf2f(src[i * LT + col]) * sc; }
	v_cndmask_b32_e64 v6, 0, 1, s[0:1]
	v_cmp_ne_u32_e64 s[4:5], 1, v6
	s_andn2_b64 vcc, exec, s[0:1]
	s_cbranch_vccnz .LBB0_608
	v_readlane_b32 s6, v252, 46
	v_readlane_b32 s7, v252, 47
	v_and_b32_e32 v7, 63, v132
	v_cndmask_b32_e64 v8, v183, v181, s[40:41]
	v_lshl_add_u32 v8, v7, 1, v8
	s_and_b64 vcc, exec, s[6:7]
	s_cbranch_vccz .Lrc_bs
	ds_read_b32 v6, v185
	ds_read_b32 v9, v185 offset:4
	ds_read_b32 v11, v185 offset:8
	ds_read_b32 v13, v185 offset:12
	ds_read_b32 v15, v185 offset:16
	ds_read_b32 v17, v185 offset:20
	ds_read_b32 v19, v185 offset:24
	ds_read_b32 v26, v185 offset:28
	ds_read_b32 v29, v185 offset:32
	ds_read_b32 v32, v185 offset:36
	ds_read_b32 v30, v185 offset:40
	ds_read_b32 v35, v185 offset:44
	ds_read_b32 v28, v185 offset:48
	ds_read_b32 v38, v185 offset:52
	ds_read_b32 v40, v185 offset:56
	ds_read_b32 v42, v185 offset:60
	ds_read_b32 v25, v185 offset:64
	ds_read_b32 v45, v185 offset:68
	ds_read_b32 v47, v185 offset:72
	ds_read_b32 v49, v185 offset:76
	ds_read_b32 v51, v185 offset:80
	ds_read_b32 v53, v185 offset:84
	ds_read_b32 v55, v185 offset:88
	ds_read_b32 v57, v185 offset:92
	ds_read_b32 v59, v185 offset:96
	ds_read_b32 v61, v185 offset:100
	ds_read_b32 v63, v185 offset:104
	ds_read_b32 v65, v185 offset:108
	ds_read_b32 v67, v185 offset:112
	ds_read_b32 v69, v185 offset:116
	ds_read_b32 v71, v185 offset:120
	ds_read_b32 v24, v185 offset:124
	ds_read_b32 v23, v185 offset:128
	ds_read_b32 v113, v185 offset:132
	ds_read_b32 v112, v185 offset:136
	ds_read_b32 v111, v185 offset:140
	ds_read_b32 v110, v185 offset:144
	ds_read_b32 v109, v185 offset:148
	ds_read_b32 v108, v185 offset:152
	ds_read_b32 v107, v185 offset:156
	ds_read_b32 v105, v185 offset:160
	ds_read_b32 v104, v185 offset:164
	ds_read_b32 v103, v185 offset:168
	ds_read_b32 v102, v185 offset:172
	ds_read_b32 v101, v185 offset:176
	ds_read_b32 v100, v185 offset:180
	ds_read_b32 v99, v185 offset:184
	ds_read_b32 v22, v185 offset:188
	ds_read_b32 v21, v185 offset:192
	ds_read_b32 v98, v185 offset:196
	ds_read_b32 v97, v185 offset:200
	ds_read_b32 v96, v185 offset:204
	ds_read_b32 v95, v185 offset:208
	ds_read_b32 v94, v185 offset:212
	ds_read_b32 v93, v185 offset:216
	ds_read_b32 v92, v185 offset:220
	ds_read_b32 v91, v185 offset:224
	ds_read_b32 v90, v185 offset:228
	ds_read_b32 v89, v185 offset:232
	ds_read_b32 v88, v185 offset:236
	ds_read_b32 v87, v185 offset:240
	ds_read_b32 v86, v185 offset:244
	ds_read_b32 v85, v185 offset:248
	ds_read_b32 v144, v185 offset:252
	ds_read_u16 v7, v8
	ds_read_u16 v10, v8 offset:144
	ds_read_u16 v12, v8 offset:288
	ds_read_u16 v14, v8 offset:432
	ds_read_u16 v16, v8 offset:576
	ds_read_u16 v18, v8 offset:720
	ds_read_u16 v20, v8 offset:864
	ds_read_u16 v27, v8 offset:1008
	ds_read_u16 v31, v8 offset:1152
	ds_read_u16 v33, v8 offset:1296
	ds_read_u16 v34, v8 offset:1440
	ds_read_u16 v36, v8 offset:1584
	ds_read_u16 v37, v8 offset:1728
	ds_read_u16 v39, v8 offset:1872
	ds_read_u16 v41, v8 offset:2016
	ds_read_u16 v43, v8 offset:2160
	ds_read_u16 v44, v8 offset:2304
	ds_read_u16 v46, v8 offset:2448
	ds_read_u16 v48, v8 offset:2592
	ds_read_u16 v50, v8 offset:2736
	ds_read_u16 v52, v8 offset:2880
	ds_read_u16 v54, v8 offset:3024
	ds_read_u16 v56, v8 offset:3168
	ds_read_u16 v58, v8 offset:3312
	ds_read_u16 v60, v8 offset:3456
	ds_read_u16 v62, v8 offset:3600
	ds_read_u16 v64, v8 offset:3744
	ds_read_u16 v66, v8 offset:3888
	ds_read_u16 v68, v8 offset:4032
	ds_read_u16 v70, v8 offset:4176
	ds_read_u16 v84, v8 offset:4320
	ds_read_u16 v114, v8 offset:4464
	ds_read_u16 v115, v8 offset:4608
	ds_read_u16 v116, v8 offset:4752
	ds_read_u16 v117, v8 offset:4896
	ds_read_u16 v118, v8 offset:5040
	ds_read_u16 v119, v8 offset:5184
	ds_read_u16 v120, v8 offset:5328
	ds_read_u16 v121, v8 offset:5472
	ds_read_u16 v122, v8 offset:5616
	ds_read_u16 v123, v8 offset:5760
	ds_read_u16 v124, v8 offset:5904
	ds_read_u16 v125, v8 offset:6048
	ds_read_u16 v126, v8 offset:6192
	ds_read_u16 v127, v8 offset:6336
	ds_read_u16 v128, v8 offset:6480
	ds_read_u16 v129, v8 offset:6624
	ds_read_u16 v133, v8 offset:6768
	ds_read_u16 v134, v8 offset:6912
	ds_read_u16 v135, v8 offset:7056
	ds_read_u16 v136, v8 offset:7200
	ds_read_u16 v137, v8 offset:7344
	ds_read_u16 v138, v8 offset:7488
	ds_read_u16 v139, v8 offset:7632
	ds_read_u16 v140, v8 offset:7776
	ds_read_u16 v141, v8 offset:7920
	ds_read_u16 v142, v8 offset:8064
	ds_read_u16 v143, v8 offset:8208
	ds_read_u16 v145, v8 offset:8352
	ds_read_u16 v146, v8 offset:8496
	ds_read_u16 v147, v8 offset:8640
	ds_read_u16 v148, v8 offset:8784
	ds_read_u16 v149, v8 offset:8928
	s_waitcnt lgkmcnt(15)
; __device__ __forceinline__ float bf2f(bf16_t b) { return __uint_as_float((unsigned)b << 16); }
; __device__ __forceinline__ float fexp(float x) { return __expf(x); }
; __device__ __forceinline__ void gdn_unit(const Ctx& X, LAS unsigned char* hl, int b, int c, int h, int tid_h, int w4, int lane, int layer) {
;     ...
;         for (int i = 0; i < 64; ++i) { const float sc = w4 == 0 ? Bs[i] : fexp(Gs[i]); rc[i] = bf2f(src[i * LT + col]) * sc; }
	v_mul_f32_e32 v6, 0x3fb8aa3b, v6
	v_exp_f32_e32 v6, v6
	v_mul_f32_e32 v9, 0x3fb8aa3b, v9
	v_exp_f32_e32 v9, v9
	v_mul_f32_e32 v11, 0x3fb8aa3b, v11
	v_exp_f32_e32 v11, v11
	v_mul_f32_e32 v13, 0x3fb8aa3b, v13
	v_exp_f32_e32 v13, v13
	v_mul_f32_e32 v15, 0x3fb8aa3b, v15
	v_exp_f32_e32 v15, v15
	v_mul_f32_e32 v17, 0x3fb8aa3b, v17
	v_exp_f32_e32 v17, v17
	v_mul_f32_e32 v19, 0x3fb8aa3b, v19
	v_exp_f32_e32 v19, v19
	v_mul_f32_e32 v26, 0x3fb8aa3b, v26
	v_exp_f32_e32 v26, v26
	v_mul_f32_e32 v29, 0x3fb8aa3b, v29
	v_exp_f32_e32 v29, v29
	v_mul_f32_e32 v32, 0x3fb8aa3b, v32
	v_exp_f32_e32 v32, v32
	v_mul_f32_e32 v30, 0x3fb8aa3b, v30
	v_exp_f32_e32 v30, v30
	v_mul_f32_e32 v35, 0x3fb8aa3b, v35
	v_exp_f32_e32 v35, v35
	v_mul_f32_e32 v28, 0x3fb8aa3b, v28
	v_exp_f32_e32 v28, v28
	v_mul_f32_e32 v38, 0x3fb8aa3b, v38
	v_exp_f32_e32 v38, v38
	v_mul_f32_e32 v40, 0x3fb8aa3b, v40
	v_exp_f32_e32 v40, v40
	v_mul_f32_e32 v42, 0x3fb8aa3b, v42
	v_exp_f32_e32 v42, v42
	v_mul_f32_e32 v25, 0x3fb8aa3b, v25
	v_exp_f32_e32 v25, v25
	v_mul_f32_e32 v45, 0x3fb8aa3b, v45
	v_exp_f32_e32 v45, v45
	v_mul_f32_e32 v47, 0x3fb8aa3b, v47
	v_exp_f32_e32 v47, v47
	v_mul_f32_e32 v49, 0x3fb8aa3b, v49
	v_exp_f32_e32 v49, v49
	v_mul_f32_e32 v51, 0x3fb8aa3b, v51
	v_exp_f32_e32 v51, v51
	v_mul_f32_e32 v53, 0x3fb8aa3b, v53
	v_exp_f32_e32 v53, v53
	v_mul_f32_e32 v55, 0x3fb8aa3b, v55
	v_exp_f32_e32 v55, v55
	v_mul_f32_e32 v57, 0x3fb8aa3b, v57
	v_exp_f32_e32 v57, v57
	v_mul_f32_e32 v59, 0x3fb8aa3b, v59
	v_exp_f32_e32 v59, v59
	v_mul_f32_e32 v61, 0x3fb8aa3b, v61
	v_exp_f32_e32 v61, v61
	v_mul_f32_e32 v63, 0x3fb8aa3b, v63
	v_exp_f32_e32 v63, v63
	v_mul_f32_e32 v65, 0x3fb8aa3b, v65
	v_exp_f32_e32 v65, v65
	v_mul_f32_e32 v67, 0x3fb8aa3b, v67
	v_exp_f32_e32 v67, v67
	v_mul_f32_e32 v69, 0x3fb8aa3b, v69
	v_exp_f32_e32 v69, v69
	v_mul_f32_e32 v71, 0x3fb8aa3b, v71
	v_exp_f32_e32 v71, v71
	v_mul_f32_e32 v24, 0x3fb8aa3b, v24
	v_exp_f32_e32 v24, v24
	v_mul_f32_e32 v23, 0x3fb8aa3b, v23
	v_exp_f32_e32 v23, v23
	v_mul_f32_e32 v113, 0x3fb8aa3b, v113
	v_exp_f32_e32 v113, v113
	v_mul_f32_e32 v112, 0x3fb8aa3b, v112
	v_exp_f32_e32 v112, v112
	v_mul_f32_e32 v111, 0x3fb8aa3b, v111
	v_exp_f32_e32 v111, v111
	v_mul_f32_e32 v110, 0x3fb8aa3b, v110
	v_exp_f32_e32 v110, v110
	v_mul_f32_e32 v109, 0x3fb8aa3b, v109
	v_exp_f32_e32 v109, v109
	v_mul_f32_e32 v108, 0x3fb8aa3b, v108
	v_exp_f32_e32 v108, v108
	v_mul_f32_e32 v107, 0x3fb8aa3b, v107
	v_exp_f32_e32 v107, v107
	v_mul_f32_e32 v105, 0x3fb8aa3b, v105
	v_exp_f32_e32 v105, v105
	v_mul_f32_e32 v104, 0x3fb8aa3b, v104
	v_exp_f32_e32 v104, v104
	v_mul_f32_e32 v103, 0x3fb8aa3b, v103
	v_exp_f32_e32 v103, v103
	v_mul_f32_e32 v102, 0x3fb8aa3b, v102
	v_exp_f32_e32 v102, v102
	v_mul_f32_e32 v101, 0x3fb8aa3b, v101
	v_exp_f32_e32 v101, v101
	v_mul_f32_e32 v100, 0x3fb8aa3b, v100
	v_exp_f32_e32 v100, v100
	v_mul_f32_e32 v99, 0x3fb8aa3b, v99
	v_exp_f32_e32 v99, v99
	v_mul_f32_e32 v22, 0x3fb8aa3b, v22
	v_exp_f32_e32 v22, v22
	v_mul_f32_e32 v21, 0x3fb8aa3b, v21
	v_exp_f32_e32 v21, v21
	v_mul_f32_e32 v98, 0x3fb8aa3b, v98
	v_exp_f32_e32 v98, v98
	v_mul_f32_e32 v97, 0x3fb8aa3b, v97
	v_exp_f32_e32 v97, v97
	v_mul_f32_e32 v96, 0x3fb8aa3b, v96
	v_exp_f32_e32 v96, v96
	v_mul_f32_e32 v95, 0x3fb8aa3b, v95
	v_exp_f32_e32 v95, v95
	v_mul_f32_e32 v94, 0x3fb8aa3b, v94
	v_exp_f32_e32 v94, v94
	v_mul_f32_e32 v93, 0x3fb8aa3b, v93
	v_exp_f32_e32 v93, v93
	v_mul_f32_e32 v92, 0x3fb8aa3b, v92
	v_exp_f32_e32 v92, v92
	v_mul_f32_e32 v91, 0x3fb8aa3b, v91
	v_exp_f32_e32 v91, v91
	v_mul_f32_e32 v90, 0x3fb8aa3b, v90
	v_exp_f32_e32 v90, v90
	v_mul_f32_e32 v89, 0x3fb8aa3b, v89
	v_exp_f32_e32 v89, v89
	v_mul_f32_e32 v88, 0x3fb8aa3b, v88
	v_exp_f32_e32 v88, v88
	v_mul_f32_e32 v87, 0x3fb8aa3b, v87
	v_exp_f32_e32 v87, v87
	v_mul_f32_e32 v86, 0x3fb8aa3b, v86
	v_exp_f32_e32 v86, v86
	v_mul_f32_e32 v85, 0x3fb8aa3b, v85
	v_exp_f32_e32 v85, v85
	v_mul_f32_e32 v144, 0x3fb8aa3b, v144
	v_exp_f32_e32 v144, v144
	s_branch .Lrc_join
